# GEMM K-loops: per-ks LDS fragment addresses hoisted to once per tile, so the MFMA phase carries no VALU at all (on top of the saddr-form in-gap prefetch)
# speedup vs baseline: 1.0692x; 1.0083x over previous
;     ...
;     for (int lt = lb; lt < per; lt += G8) {
;         const int grp = lt / (8 * nNt), q = lt - grp * 8 * nNt, gs = (mper - grp * 8) < 8 ? (mper - grp * 8) : 8;
;         const int tn = q / gs, tm = xcd * mper + grp * 8 + (q - tn * gs);
;         const bf16_t* Au = A + (size_t)(tm * 128) * lda;
;         const bf16_t* Bu = Bt + (size_t)(tn * 256) * ldb;
;         const unsigned voA = (unsigned)(lr * lda + lc * 8), voB = (unsigned)(lr * ldb + lc * 8);
;         f32x16 acc[2][4];
; #pragma unroll
;         for (int i = 0; i < 2; ++i)
; #pragma unroll
;             for (int j = 0; j < 4; ++j)
; #pragma unroll
;                 for (int r = 0; r < 16; ++r) acc[i][j][r] = 0.f;
;         u32x4 ra[4], rb[8];
; #pragma unroll
;         for (int i = 0; i < 4; ++i) ra[i] = *(const u32x4*)((Au + (size_t)(32 * i) * lda) + voA);
; #pragma unroll
;         for (int i = 0; i < 8; ++i) rb[i] = *(const u32x4*)((Bu + (size_t)(32 * i) * ldb) + voB);
;     ...
;                 const unsigned xo = (c0 ^ (unsigned)(2 * ks)) << 4;
; #pragma unroll
;                 for (int i = 0; i < 2; ++i) af[i] = *(const bf16x8*)(lds + (roA + xo) + i * 4096);
; #pragma unroll
;                 for (int j = 0; j < 4; ++j) bfr[j] = *(const bf16x8*)(lds + (roB + xo) + j * 4096);
.LBB0_140:
	s_mul_hi_i32 s4, s93, 0x2aaaaaab
	s_lshr_b32 s5, s4, 31
	s_ashr_i32 s4, s4, 3
	s_add_i32 s4, s4, s5
	s_lshl_b32 s5, s4, 3
	s_mulk_i32 s4, 0xffd0
	s_add_i32 s4, s4, s93
	s_sub_i32 s6, 0x42, s5
	s_cmpk_gt_i32 s93, 0x17f
	s_cselect_b32 s6, s6, 8
	s_abs_i32 s7, s6
	v_cvt_f32_u32_e32 v0, s7
	s_sub_i32 s10, 0, s7
	s_abs_i32 s8, s4
	s_xor_b32 s9, s4, s6
	v_rcp_iflag_f32_e32 v0, v0
	s_ashr_i32 s9, s9, 31
	v_mov_b32_e32 v14, v1
	v_mov_b32_e32 v15, v1
	v_mul_f32_e32 v0, 0x4f7ffffe, v0
	v_cvt_u32_f32_e32 v0, v0
	v_mov_b32_e32 v6, v1
	v_mov_b32_e32 v7, v1
	v_mov_b32_e32 v8, v1
	v_readfirstlane_b32 s11, v0
	s_mul_i32 s10, s10, s11
	s_mul_hi_u32 s10, s11, s10
	s_add_i32 s11, s11, s10
	s_mul_hi_u32 s10, s8, s11
	s_mul_i32 s11, s10, s7
	s_sub_i32 s8, s8, s11
	s_add_i32 s18, s10, 1
	s_sub_i32 s11, s8, s7
	s_cmp_ge_u32 s8, s7
	s_cselect_b32 s10, s18, s10
	s_cselect_b32 s8, s11, s8
	s_add_i32 s11, s10, 1
	s_cmp_ge_u32 s8, s7
	s_cselect_b32 s7, s11, s10
	s_xor_b32 s7, s7, s9
	s_sub_i32 s7, s7, s9
	s_add_i32 s5, s5, s3
	s_mul_i32 s6, s6, s7
	s_add_i32 s5, s5, s4
	s_sub_i32 s4, s5, s6
	s_lshl_b32 s4, s4, 7
	s_ashr_i32 s5, s4, 31
	s_lshl_b64 s[8:9], s[4:5], 11
	v_lshl_add_u64 v[182:183], v[178:179], 0, s[8:9]
	v_add_co_u32_e32 v2, vcc, s70, v182
	s_lshl_b32 s6, s7, 8
	s_nop 0
	v_addc_co_u32_e32 v3, vcc, 0, v183, vcc
	v_add_co_u32_e32 v4, vcc, s71, v182
	s_ashr_i32 s7, s6, 31
	s_nop 0
	v_addc_co_u32_e32 v5, vcc, 0, v183, vcc
	s_lshl_b64 s[18:19], s[6:7], 11
	global_load_dwordx4 v[130:133], v[2:3], off
	global_load_dwordx4 v[138:141], v[4:5], off
	v_add_co_u32_e32 v2, vcc, s74, v182
	v_lshl_add_u64 v[184:185], v[180:181], 0, s[18:19]
	s_nop 0
	v_addc_co_u32_e32 v3, vcc, 0, v183, vcc
	v_add_co_u32_e32 v4, vcc, s70, v184
	global_load_dwordx4 v[134:137], v[182:183], off
	global_load_dwordx4 v[146:149], v[184:185], off
	v_addc_co_u32_e32 v5, vcc, 0, v185, vcc
	global_load_dwordx4 v[142:145], v[2:3], off
	global_load_dwordx4 v[150:153], v[4:5], off
	v_add_co_u32_e32 v2, vcc, s71, v184
	v_mov_b32_e32 v0, v1
	s_nop 0
	v_addc_co_u32_e32 v3, vcc, 0, v185, vcc
	v_add_co_u32_e32 v4, vcc, s74, v184
	v_mov_b32_e32 v9, v1
	s_nop 0
	v_addc_co_u32_e32 v5, vcc, 0, v185, vcc
	global_load_dwordx4 v[154:157], v[2:3], off
	global_load_dwordx4 v[158:161], v[4:5], off
	v_add_co_u32_e32 v2, vcc, s75, v184
	v_mov_b32_e32 v10, v1
	s_nop 0
	v_addc_co_u32_e32 v3, vcc, 0, v185, vcc
	v_add_co_u32_e32 v4, vcc, 0x50000, v184
	v_mov_b32_e32 v11, v1
	s_nop 0
	v_addc_co_u32_e32 v5, vcc, 0, v185, vcc
	global_load_dwordx4 v[162:165], v[2:3], off
	global_load_dwordx4 v[166:169], v[4:5], off
	v_add_co_u32_e32 v2, vcc, 0x60000, v184
	v_mov_b32_e32 v12, v1
	s_nop 0
	v_addc_co_u32_e32 v3, vcc, 0, v185, vcc
	v_add_co_u32_e32 v4, vcc, 0x70000, v184
	v_mov_b32_e32 v13, v1
	s_nop 0
	v_addc_co_u32_e32 v5, vcc, 0, v185, vcc
	global_load_dwordx4 v[170:173], v[2:3], off
	global_load_dwordx4 v[174:177], v[4:5], off
	v_mov_b32_e32 v2, v1
	v_mov_b32_e32 v3, v1
	v_mov_b32_e32 v4, v1
	v_mov_b32_e32 v5, v1
	v_mov_b64_e32 v[96:97], v[14:15]
	v_mov_b64_e32 v[128:129], v[14:15]
	v_mov_b64_e32 v[112:113], v[14:15]
	v_mov_b64_e32 v[80:81], v[14:15]
	v_mov_b64_e32 v[64:65], v[14:15]
	v_mov_b64_e32 v[48:49], v[14:15]
	v_mov_b64_e32 v[32:33], v[14:15]
	v_mov_b64_e32 v[94:95], v[12:13]
	v_mov_b64_e32 v[92:93], v[10:11]
	v_mov_b64_e32 v[90:91], v[8:9]
	v_mov_b64_e32 v[88:89], v[6:7]
	v_mov_b64_e32 v[86:87], v[4:5]
	v_mov_b64_e32 v[84:85], v[2:3]
	v_mov_b64_e32 v[82:83], v[0:1]
	v_mov_b64_e32 v[126:127], v[12:13]
	v_mov_b64_e32 v[124:125], v[10:11]
	v_mov_b64_e32 v[122:123], v[8:9]
	v_mov_b64_e32 v[120:121], v[6:7]
	v_mov_b64_e32 v[118:119], v[4:5]
	v_mov_b64_e32 v[116:117], v[2:3]
	v_mov_b64_e32 v[114:115], v[0:1]
	v_mov_b64_e32 v[110:111], v[12:13]
	v_mov_b64_e32 v[108:109], v[10:11]
	v_mov_b64_e32 v[106:107], v[8:9]
	v_mov_b64_e32 v[104:105], v[6:7]
	v_mov_b64_e32 v[102:103], v[4:5]
	v_mov_b64_e32 v[100:101], v[2:3]
	v_mov_b64_e32 v[98:99], v[0:1]
	v_mov_b64_e32 v[78:79], v[12:13]
	v_mov_b64_e32 v[76:77], v[10:11]
	v_mov_b64_e32 v[74:75], v[8:9]
	v_mov_b64_e32 v[72:73], v[6:7]
	v_mov_b64_e32 v[70:71], v[4:5]
	v_mov_b64_e32 v[68:69], v[2:3]
	v_mov_b64_e32 v[66:67], v[0:1]
	v_mov_b64_e32 v[62:63], v[12:13]
	v_mov_b64_e32 v[60:61], v[10:11]
	v_mov_b64_e32 v[58:59], v[8:9]
	v_mov_b64_e32 v[56:57], v[6:7]
	v_mov_b64_e32 v[54:55], v[4:5]
	v_mov_b64_e32 v[52:53], v[2:3]
	v_mov_b64_e32 v[50:51], v[0:1]
	v_mov_b64_e32 v[46:47], v[12:13]
	v_mov_b64_e32 v[44:45], v[10:11]
	v_mov_b64_e32 v[42:43], v[8:9]
	v_mov_b64_e32 v[40:41], v[6:7]
	v_mov_b64_e32 v[38:39], v[4:5]
	v_mov_b64_e32 v[36:37], v[2:3]
	v_mov_b64_e32 v[34:35], v[0:1]
	v_mov_b64_e32 v[30:31], v[12:13]
	v_mov_b64_e32 v[28:29], v[10:11]
	v_mov_b64_e32 v[26:27], v[8:9]
	v_mov_b64_e32 v[24:25], v[6:7]
	v_mov_b64_e32 v[22:23], v[4:5]
	v_mov_b64_e32 v[20:21], v[2:3]
	v_mov_b64_e32 v[18:19], v[0:1]
	v_mov_b64_e32 v[16:17], v[14:15]
	v_mov_b64_e32 v[14:15], v[12:13]
	v_mov_b64_e32 v[12:13], v[10:11]
	v_mov_b64_e32 v[10:11], v[8:9]
	v_mov_b64_e32 v[8:9], v[6:7]
	v_mov_b64_e32 v[6:7], v[4:5]
	v_mov_b64_e32 v[4:5], v[2:3]
	v_mov_b64_e32 v[2:3], v[0:1]
	s_mov_b32 s5, s31
	v_readfirstlane_b32 s22, v182
	v_readfirstlane_b32 s23, v183
	v_readfirstlane_b32 s96, v184
	v_readfirstlane_b32 s97, v185
	v_subrev_u32_e32 v228, s22, v182
	v_subrev_u32_e32 v229, s96, v184
	v_xor_b32_e32 v231, 0, v187
	v_add_u32_e32 v230, v188, v231
	v_add_u32_e32 v231, v189, v231
	v_xor_b32_e32 v233, 32, v187
	v_add_u32_e32 v232, v188, v233
	v_add_u32_e32 v233, v189, v233
	v_xor_b32_e32 v235, 64, v187
	v_add_u32_e32 v234, v188, v235
	v_add_u32_e32 v235, v189, v235
	v_xor_b32_e32 v237, 0x60, v187
	v_add_u32_e32 v236, v188, v237
	v_add_u32_e32 v237, v189, v237
; DI unsigned swz(int row, int chunk) { return (unsigned)row * 128u + (unsigned)((chunk ^ ((row >> 1) & 7)) << 4); }
; #define MFMA32(a, b, c) __builtin_amdgcn_mfma_f32_32x32x16_bf16((a), (b), (c), 0, 0, 0)
;     ...
;         for (int kt = 0; kt < nk; ++kt) {
; #pragma unroll
;             for (int i = 0; i < 4; ++i) *(u32x4*)(lds + swz(lr + 32 * i, lc)) = ra[i];
; #pragma unroll
;             for (int i = 0; i < 8; ++i) *(u32x4*)(lds + 16384 + swz(lr + 32 * i, lc)) = rb[i];
;             __syncthreads();
;             if (kt + 1 < nk) {
; #pragma unroll
;                 for (int i = 0; i < 4; ++i) ra[i] = *(const u32x4*)((Au + (size_t)(32 * i) * lda + (kt + 1) * 64) + voA);
; #pragma unroll
;                 for (int i = 0; i < 8; ++i) rb[i] = *(const u32x4*)((Bu + (size_t)(32 * i) * ldb + (kt + 1) * 64) + voB);
;             }
;             __builtin_amdgcn_s_setprio(1);
; #pragma unroll 2
;             for (int ks = 0; ks < 4; ++ks) {
;                 bf16x8 af[2], bfr[4];
;                 const unsigned xo = (c0 ^ (unsigned)(2 * ks)) << 4;
; #pragma unroll
;                 for (int i = 0; i < 2; ++i) af[i] = *(const bf16x8*)(lds + (roA + xo) + i * 4096);
; #pragma unroll
;                 for (int j = 0; j < 4; ++j) bfr[j] = *(const bf16x8*)(lds + (roB + xo) + j * 4096);
; #pragma unroll
;                 for (int i = 0; i < 2; ++i)
; #pragma unroll
;                     for (int j = 0; j < 4; ++j) acc[i][j] = MFMA32(af[i], bfr[j], acc[i][j]);
;             }
;             __builtin_amdgcn_s_setprio(0);
;             __syncthreads();
.LBB0_141:
	s_mov_b32 s7, s5
	s_add_i32 s5, s5, 1
	s_cmp_lg_u32 s7, 15
	s_waitcnt vmcnt(9)
	ds_write_b128 v192, v[134:137]
	ds_write_b128 v192, v[130:133] offset:4096
	ds_write_b128 v192, v[138:141] offset:8192
	s_waitcnt vmcnt(7)
	ds_write_b128 v192, v[142:145] offset:12288
	ds_write_b128 v192, v[146:149] offset:16384
	s_waitcnt vmcnt(6)
	ds_write_b128 v192, v[150:153] offset:20480
	s_waitcnt vmcnt(5)
	ds_write_b128 v192, v[154:157] offset:24576
	s_waitcnt vmcnt(4)
	ds_write_b128 v192, v[158:161] offset:28672
	s_waitcnt vmcnt(3)
	ds_write_b128 v192, v[162:165] offset:32768
	s_waitcnt vmcnt(2)
	ds_write_b128 v192, v[166:169] offset:36864
	s_waitcnt vmcnt(1)
	ds_write_b128 v192, v[170:173] offset:40960
	s_waitcnt vmcnt(0)
	ds_write_b128 v192, v[174:177] offset:45056
	s_waitcnt lgkmcnt(0)
	s_barrier
	s_cbranch_scc0 .LBB0_143
	s_lshl_b32 s14, s5, 7
	s_setprio 1
	ds_read_b128 v[196:199], v230
	ds_read_b128 v[200:203], v231 offset:16384
	ds_read_b128 v[204:207], v230 offset:4096
	ds_read_b128 v[208:211], v231 offset:20480
	ds_read_b128 v[212:215], v231 offset:24576
	ds_read_b128 v[218:221], v231 offset:28672
	s_waitcnt lgkmcnt(4)
	v_mfma_f32_32x32x16_bf16 v[114:129], v[196:199], v[200:203], v[114:129]
	s_add_u32 s14, s22, s14
	s_addc_u32 s15, s23, 0
	global_load_dwordx4 v[134:137], v228, s[14:15]
	s_add_u32 s14, s14, 0x10000
	s_addc_u32 s15, s15, 0
	s_waitcnt lgkmcnt(2)
	v_mfma_f32_32x32x16_bf16 v[82:97], v[196:199], v[208:211], v[82:97]
	s_waitcnt lgkmcnt(1)
	v_mfma_f32_32x32x16_bf16 v[98:113], v[196:199], v[212:215], v[98:113]
	global_load_dwordx4 v[130:133], v228, s[14:15]
	s_add_u32 s14, s14, 0x10000
	s_addc_u32 s15, s15, 0
	s_waitcnt lgkmcnt(0)
	v_mfma_f32_32x32x16_bf16 v[66:81], v[196:199], v[218:221], v[66:81]
	v_mfma_f32_32x32x16_bf16 v[50:65], v[204:207], v[200:203], v[50:65]
	global_load_dwordx4 v[138:141], v228, s[14:15]
	s_add_u32 s14, s14, 0x10000
	s_addc_u32 s15, s15, 0
	v_mfma_f32_32x32x16_bf16 v[34:49], v[204:207], v[208:211], v[34:49]
	v_mfma_f32_32x32x16_bf16 v[18:33], v[204:207], v[212:215], v[18:33]
	global_load_dwordx4 v[142:145], v228, s[14:15]
	v_mfma_f32_32x32x16_bf16 v[2:17], v[204:207], v[218:221], v[2:17]
	ds_read_b128 v[196:199], v232
	ds_read_b128 v[200:203], v233 offset:16384
	ds_read_b128 v[204:207], v232 offset:4096
	ds_read_b128 v[208:211], v233 offset:20480
	ds_read_b128 v[212:215], v233 offset:24576
	ds_read_b128 v[218:221], v233 offset:28672
	s_waitcnt lgkmcnt(4)
	v_mfma_f32_32x32x16_bf16 v[114:129], v[196:199], v[200:203], v[114:129]
	s_lshl_b32 s14, s5, 7
	s_add_u32 s14, s96, s14
	s_addc_u32 s15, s97, 0
	global_load_dwordx4 v[146:149], v229, s[14:15]
	s_add_u32 s14, s14, 0x10000
	s_addc_u32 s15, s15, 0
	s_waitcnt lgkmcnt(2)
	v_mfma_f32_32x32x16_bf16 v[82:97], v[196:199], v[208:211], v[82:97]
	s_waitcnt lgkmcnt(1)
	v_mfma_f32_32x32x16_bf16 v[98:113], v[196:199], v[212:215], v[98:113]
	global_load_dwordx4 v[150:153], v229, s[14:15]
	s_add_u32 s14, s14, 0x10000
	s_addc_u32 s15, s15, 0
	s_waitcnt lgkmcnt(0)
	v_mfma_f32_32x32x16_bf16 v[66:81], v[196:199], v[218:221], v[66:81]
	v_mfma_f32_32x32x16_bf16 v[50:65], v[204:207], v[200:203], v[50:65]
	global_load_dwordx4 v[154:157], v229, s[14:15]
	s_add_u32 s14, s14, 0x10000
	s_addc_u32 s15, s15, 0
	v_mfma_f32_32x32x16_bf16 v[34:49], v[204:207], v[208:211], v[34:49]
	v_mfma_f32_32x32x16_bf16 v[18:33], v[204:207], v[212:215], v[18:33]
	global_load_dwordx4 v[158:161], v229, s[14:15]
	s_add_u32 s14, s14, 0x10000
	s_addc_u32 s15, s15, 0
	v_mfma_f32_32x32x16_bf16 v[2:17], v[204:207], v[218:221], v[2:17]
	ds_read_b128 v[196:199], v234
	ds_read_b128 v[200:203], v235 offset:16384
	ds_read_b128 v[204:207], v234 offset:4096
	ds_read_b128 v[208:211], v235 offset:20480
	ds_read_b128 v[212:215], v235 offset:24576
	ds_read_b128 v[218:221], v235 offset:28672
	s_waitcnt lgkmcnt(4)
	v_mfma_f32_32x32x16_bf16 v[114:129], v[196:199], v[200:203], v[114:129]
	global_load_dwordx4 v[162:165], v229, s[14:15]
	s_add_u32 s14, s14, 0x10000
	s_addc_u32 s15, s15, 0
	s_waitcnt lgkmcnt(2)
	v_mfma_f32_32x32x16_bf16 v[82:97], v[196:199], v[208:211], v[82:97]
	s_waitcnt lgkmcnt(1)
	v_mfma_f32_32x32x16_bf16 v[98:113], v[196:199], v[212:215], v[98:113]
	global_load_dwordx4 v[166:169], v229, s[14:15]
	s_add_u32 s14, s14, 0x10000
	s_addc_u32 s15, s15, 0
	s_waitcnt lgkmcnt(0)
	v_mfma_f32_32x32x16_bf16 v[66:81], v[196:199], v[218:221], v[66:81]
	v_mfma_f32_32x32x16_bf16 v[50:65], v[204:207], v[200:203], v[50:65]
	global_load_dwordx4 v[170:173], v229, s[14:15]
	s_add_u32 s14, s14, 0x10000
	s_addc_u32 s15, s15, 0
	v_mfma_f32_32x32x16_bf16 v[34:49], v[204:207], v[208:211], v[34:49]
	v_mfma_f32_32x32x16_bf16 v[18:33], v[204:207], v[212:215], v[18:33]
	global_load_dwordx4 v[174:177], v229, s[14:15]
	v_mfma_f32_32x32x16_bf16 v[2:17], v[204:207], v[218:221], v[2:17]
	ds_read_b128 v[196:199], v236
	ds_read_b128 v[200:203], v237 offset:16384
	ds_read_b128 v[204:207], v236 offset:4096
	ds_read_b128 v[208:211], v237 offset:20480
	ds_read_b128 v[212:215], v237 offset:24576
	ds_read_b128 v[218:221], v237 offset:28672
	s_waitcnt lgkmcnt(4)
	v_mfma_f32_32x32x16_bf16 v[114:129], v[196:199], v[200:203], v[114:129]
	s_waitcnt lgkmcnt(2)
	v_mfma_f32_32x32x16_bf16 v[82:97], v[196:199], v[208:211], v[82:97]
	s_waitcnt lgkmcnt(1)
	v_mfma_f32_32x32x16_bf16 v[98:113], v[196:199], v[212:215], v[98:113]
	s_waitcnt lgkmcnt(0)
	v_mfma_f32_32x32x16_bf16 v[66:81], v[196:199], v[218:221], v[66:81]
	v_mfma_f32_32x32x16_bf16 v[50:65], v[204:207], v[200:203], v[50:65]
	v_mfma_f32_32x32x16_bf16 v[34:49], v[204:207], v[208:211], v[34:49]
	v_mfma_f32_32x32x16_bf16 v[18:33], v[204:207], v[212:215], v[18:33]
	v_mfma_f32_32x32x16_bf16 v[2:17], v[204:207], v[218:221], v[2:17]
	s_branch .Lkint_done_144

;     ...
;     for (int lt = lb; lt < per; lt += G8) {
;         const int grp = lt / (8 * nNt), q = lt - grp * 8 * nNt, gs = (mper - grp * 8) < 8 ? (mper - grp * 8) : 8;
;         const int tn = q / gs, tm = xcd * mper + grp * 8 + (q - tn * gs);
;         const bf16_t* Au = A + (size_t)(tm * 128) * lda;
;         const bf16_t* Bu = Bt + (size_t)(tn * 256) * ldb;
;         const unsigned voA = (unsigned)(lr * lda + lc * 8), voB = (unsigned)(lr * ldb + lc * 8);
;         f32x16 acc[2][4];
; #pragma unroll
;         for (int i = 0; i < 2; ++i)
; #pragma unroll
;             for (int j = 0; j < 4; ++j)
; #pragma unroll
;                 for (int r = 0; r < 16; ++r) acc[i][j][r] = 0.f;
;         u32x4 ra[4], rb[8];
; #pragma unroll
;         for (int i = 0; i < 4; ++i) ra[i] = *(const u32x4*)((Au + (size_t)(32 * i) * lda) + voA);
; #pragma unroll
;         for (int i = 0; i < 8; ++i) rb[i] = *(const u32x4*)((Bu + (size_t)(32 * i) * ldb) + voB);
;     ...
;                 const unsigned xo = (c0 ^ (unsigned)(2 * ks)) << 4;
; #pragma unroll
;                 for (int i = 0; i < 2; ++i) af[i] = *(const bf16x8*)(lds + (roA + xo) + i * 4096);
; #pragma unroll
;                 for (int j = 0; j < 4; ++j) bfr[j] = *(const bf16x8*)(lds + (roB + xo) + j * 4096);
.LBB0_643:
	s_ashr_i32 s4, s97, 31
	s_lshr_b32 s4, s4, 27
	s_add_i32 s4, s97, s4
	s_ashr_i32 s6, s4, 5
	s_lshl_b32 s6, s6, 3
	s_sub_i32 s7, 0x42, s6
	s_min_u32 s7, s7, 8
	v_cvt_f32_ubyte0_e32 v1, s7
	v_rcp_iflag_f32_e32 v1, v1
	s_sub_i32 s10, 0, s7
	s_andn2_b32 s4, s4, 31
	s_sub_i32 s4, s97, s4
	v_mul_f32_e32 v1, 0x4f7ffffe, v1
	v_cvt_u32_f32_e32 v1, v1
	s_abs_i32 s9, s4
	s_ashr_i32 s8, s4, 31
	v_mov_b32_e32 v14, v0
	v_readfirstlane_b32 s11, v1
	s_mul_i32 s10, s10, s11
	s_mul_hi_u32 s10, s11, s10
	s_add_i32 s11, s11, s10
	s_mul_hi_u32 s10, s9, s11
	s_mul_i32 s11, s10, s7
	s_sub_i32 s9, s9, s11
	s_add_i32 s18, s10, 1
	s_sub_i32 s11, s9, s7
	s_cmp_ge_u32 s9, s7
	s_cselect_b32 s10, s18, s10
	s_cselect_b32 s9, s11, s9
	s_add_i32 s11, s10, 1
	s_cmp_ge_u32 s9, s7
	s_cselect_b32 s9, s11, s10
	s_xor_b32 s9, s9, s8
	s_sub_i32 s8, s9, s8
	s_add_i32 s6, s6, s3
	s_mul_i32 s7, s7, s8
	s_add_i32 s6, s6, s4
	s_sub_i32 s4, s6, s7
	s_lshl_b32 s6, s4, 7
	s_ashr_i32 s7, s6, 31
	s_lshl_b32 s8, s8, 8
	s_ashr_i32 s9, s8, 31
	s_lshl_b64 s[18:19], s[6:7], 11
	v_lshl_add_u64 v[182:183], v[178:179], 0, s[18:19]
	s_lshl_b64 s[18:19], s[8:9], 11
	v_lshl_add_u64 v[184:185], v[180:181], 0, s[18:19]
	s_mov_b32 s4, 0x70000
	v_add_co_u32_e32 v2, vcc, s4, v184
	s_mov_b32 s4, 0x60000
	s_nop 0
	v_addc_co_u32_e32 v3, vcc, 0, v185, vcc
	v_add_co_u32_e32 v4, vcc, s4, v184
	s_mov_b32 s4, 0x50000
	s_nop 0
	v_addc_co_u32_e32 v5, vcc, 0, v185, vcc
	global_load_dwordx4 v[142:145], v[2:3], off
	global_load_dwordx4 v[146:149], v[4:5], off
	v_add_co_u32_e32 v2, vcc, s4, v184
	s_mov_b32 s4, 0x40000
	s_nop 0
	v_addc_co_u32_e32 v3, vcc, 0, v185, vcc
	v_add_co_u32_e32 v4, vcc, s4, v184
	v_mov_b32_e32 v15, v0
	s_nop 0
	v_addc_co_u32_e32 v5, vcc, 0, v185, vcc
	global_load_dwordx4 v[150:153], v[2:3], off
	global_load_dwordx4 v[154:157], v[4:5], off
	v_add_co_u32_e32 v2, vcc, s14, v184
	v_mov_b32_e32 v1, v0
	s_nop 0
	v_addc_co_u32_e32 v3, vcc, 0, v185, vcc
	v_add_co_u32_e32 v4, vcc, 0x20000, v184
	v_mov_b32_e32 v6, v0
	s_nop 0
	v_addc_co_u32_e32 v5, vcc, 0, v185, vcc
	global_load_dwordx4 v[158:161], v[2:3], off
	global_load_dwordx4 v[162:165], v[4:5], off
	v_add_co_u32_e32 v2, vcc, 0x10000, v184
	v_mov_b32_e32 v7, v0
	s_nop 0
	v_addc_co_u32_e32 v3, vcc, 0, v185, vcc
	v_add_co_u32_e32 v4, vcc, 0x30000, v182
	v_mov_b32_e32 v8, v0
	s_nop 0
	v_addc_co_u32_e32 v5, vcc, 0, v183, vcc
	global_load_dwordx4 v[166:169], v[2:3], off
	global_load_dwordx4 v[134:137], v[4:5], off
	v_add_co_u32_e32 v2, vcc, 0x20000, v182
	v_mov_b32_e32 v9, v0
	s_nop 0
	v_addc_co_u32_e32 v3, vcc, 0, v183, vcc
	v_add_co_u32_e32 v4, vcc, 0x10000, v182
	v_mov_b32_e32 v10, v0
	s_nop 0
	v_addc_co_u32_e32 v5, vcc, 0, v183, vcc
	global_load_dwordx4 v[170:173], v[2:3], off
	global_load_dwordx4 v[138:141], v[4:5], off
	global_load_dwordx4 v[174:177], v[184:185], off
	global_load_dwordx4 v[130:133], v[182:183], off
	v_mov_b32_e32 v2, v0
	v_mov_b32_e32 v3, v0
	v_mov_b32_e32 v4, v0
	v_mov_b32_e32 v5, v0
	v_mov_b32_e32 v11, v0
	v_mov_b32_e32 v12, v0
	v_mov_b32_e32 v13, v0
	s_waitcnt vmcnt(20)
	v_mov_b64_e32 v[96:97], v[14:15]
	v_mov_b64_e32 v[128:129], v[14:15]
	v_mov_b64_e32 v[64:65], v[14:15]
	v_mov_b64_e32 v[32:33], v[14:15]
	v_mov_b64_e32 v[112:113], v[14:15]
	v_mov_b64_e32 v[80:81], v[14:15]
	v_mov_b64_e32 v[48:49], v[14:15]
	v_mov_b64_e32 v[94:95], v[12:13]
	v_mov_b64_e32 v[92:93], v[10:11]
	v_mov_b64_e32 v[90:91], v[8:9]
	v_mov_b64_e32 v[88:89], v[6:7]
	v_mov_b64_e32 v[86:87], v[4:5]
	v_mov_b64_e32 v[84:85], v[2:3]
	v_mov_b64_e32 v[82:83], v[0:1]
	v_mov_b64_e32 v[126:127], v[12:13]
	v_mov_b64_e32 v[124:125], v[10:11]
	v_mov_b64_e32 v[122:123], v[8:9]
	v_mov_b64_e32 v[120:121], v[6:7]
	v_mov_b64_e32 v[118:119], v[4:5]
	v_mov_b64_e32 v[116:117], v[2:3]
	v_mov_b64_e32 v[114:115], v[0:1]
	v_mov_b64_e32 v[62:63], v[12:13]
	v_mov_b64_e32 v[60:61], v[10:11]
	v_mov_b64_e32 v[58:59], v[8:9]
	v_mov_b64_e32 v[56:57], v[6:7]
	v_mov_b64_e32 v[54:55], v[4:5]
	v_mov_b64_e32 v[52:53], v[2:3]
	v_mov_b64_e32 v[50:51], v[0:1]
	v_mov_b64_e32 v[30:31], v[12:13]
	v_mov_b64_e32 v[28:29], v[10:11]
	v_mov_b64_e32 v[26:27], v[8:9]
	v_mov_b64_e32 v[24:25], v[6:7]
	v_mov_b64_e32 v[22:23], v[4:5]
	v_mov_b64_e32 v[20:21], v[2:3]
	v_mov_b64_e32 v[18:19], v[0:1]
	v_mov_b64_e32 v[110:111], v[12:13]
	v_mov_b64_e32 v[108:109], v[10:11]
	v_mov_b64_e32 v[106:107], v[8:9]
	v_mov_b64_e32 v[104:105], v[6:7]
	v_mov_b64_e32 v[102:103], v[4:5]
	v_mov_b64_e32 v[100:101], v[2:3]
	v_mov_b64_e32 v[98:99], v[0:1]
	v_mov_b64_e32 v[78:79], v[12:13]
	v_mov_b64_e32 v[76:77], v[10:11]
	v_mov_b64_e32 v[74:75], v[8:9]
	v_mov_b64_e32 v[72:73], v[6:7]
	v_mov_b64_e32 v[70:71], v[4:5]
	v_mov_b64_e32 v[68:69], v[2:3]
	v_mov_b64_e32 v[66:67], v[0:1]
	v_mov_b64_e32 v[46:47], v[12:13]
	v_mov_b64_e32 v[44:45], v[10:11]
	v_mov_b64_e32 v[42:43], v[8:9]
	v_mov_b64_e32 v[40:41], v[6:7]
	v_mov_b64_e32 v[38:39], v[4:5]
	v_mov_b64_e32 v[36:37], v[2:3]
	v_mov_b64_e32 v[34:35], v[0:1]
	v_mov_b64_e32 v[16:17], v[14:15]
	v_mov_b64_e32 v[14:15], v[12:13]
	v_mov_b64_e32 v[12:13], v[10:11]
	v_mov_b64_e32 v[10:11], v[8:9]
	v_mov_b64_e32 v[8:9], v[6:7]
	v_mov_b64_e32 v[6:7], v[4:5]
	v_mov_b64_e32 v[4:5], v[2:3]
	v_mov_b64_e32 v[2:3], v[0:1]
	s_mov_b32 s7, s5
	v_readfirstlane_b32 s18, v182
	v_readfirstlane_b32 s19, v183
	v_readfirstlane_b32 s22, v184
	v_readfirstlane_b32 s23, v185
	v_subrev_u32_e32 v226, s18, v182
	v_subrev_u32_e32 v227, s22, v184
	v_xor_b32_e32 v229, 0, v219
	v_add_u32_e32 v228, v220, v229
	v_add_u32_e32 v229, v221, v229
	v_xor_b32_e32 v231, 32, v219
	v_add_u32_e32 v230, v220, v231
	v_add_u32_e32 v231, v221, v231
	v_xor_b32_e32 v233, 64, v219
	v_add_u32_e32 v232, v220, v233
	v_add_u32_e32 v233, v221, v233
	v_xor_b32_e32 v235, 0x60, v219
	v_add_u32_e32 v234, v220, v235
	v_add_u32_e32 v235, v221, v235
; DI unsigned swz(int row, int chunk) { return (unsigned)row * 128u + (unsigned)((chunk ^ ((row >> 1) & 7)) << 4); }
; #define MFMA32(a, b, c) __builtin_amdgcn_mfma_f32_32x32x16_bf16((a), (b), (c), 0, 0, 0)
;     ...
;         for (int kt = 0; kt < nk; ++kt) {
; #pragma unroll
;             for (int i = 0; i < 4; ++i) *(u32x4*)(lds + swz(lr + 32 * i, lc)) = ra[i];
; #pragma unroll
;             for (int i = 0; i < 8; ++i) *(u32x4*)(lds + 16384 + swz(lr + 32 * i, lc)) = rb[i];
;             __syncthreads();
;             if (kt + 1 < nk) {
; #pragma unroll
;                 for (int i = 0; i < 4; ++i) ra[i] = *(const u32x4*)((Au + (size_t)(32 * i) * lda + (kt + 1) * 64) + voA);
; #pragma unroll
;                 for (int i = 0; i < 8; ++i) rb[i] = *(const u32x4*)((Bu + (size_t)(32 * i) * ldb + (kt + 1) * 64) + voB);
;             }
;             __builtin_amdgcn_s_setprio(1);
; #pragma unroll 2
;             for (int ks = 0; ks < 4; ++ks) {
;                 bf16x8 af[2], bfr[4];
;                 const unsigned xo = (c0 ^ (unsigned)(2 * ks)) << 4;
; #pragma unroll
;                 for (int i = 0; i < 2; ++i) af[i] = *(const bf16x8*)(lds + (roA + xo) + i * 4096);
; #pragma unroll
;                 for (int j = 0; j < 4; ++j) bfr[j] = *(const bf16x8*)(lds + (roB + xo) + j * 4096);
; #pragma unroll
;                 for (int i = 0; i < 2; ++i)
; #pragma unroll
;                     for (int j = 0; j < 4; ++j) acc[i][j] = MFMA32(af[i], bfr[j], acc[i][j]);
;             }
;             __builtin_amdgcn_s_setprio(0);
;             __syncthreads();
.LBB0_644:
	s_mov_b32 s4, s7
	s_add_i32 s7, s7, 1
	s_cmp_lt_u32 s4, 15
	s_waitcnt vmcnt(0)
	ds_write_b128 v224, v[130:133]
	ds_write_b128 v224, v[138:141] offset:4096
	ds_write_b128 v224, v[170:173] offset:8192
	ds_write_b128 v224, v[134:137] offset:12288
	ds_write_b128 v224, v[174:177] offset:16384
	ds_write_b128 v224, v[166:169] offset:20480
	ds_write_b128 v224, v[162:165] offset:24576
	ds_write_b128 v224, v[158:161] offset:28672
	ds_write_b128 v224, v[154:157] offset:32768
	ds_write_b128 v224, v[150:153] offset:36864
	ds_write_b128 v224, v[146:149] offset:40960
	ds_write_b128 v224, v[142:145] offset:45056
	s_waitcnt lgkmcnt(0)
	s_barrier
	s_cbranch_scc0 .LBB0_646
	s_lshl_b32 s10, s7, 7
	s_setprio 1
	ds_read_b128 v[186:189], v228
	ds_read_b128 v[190:193], v229 offset:16384
	ds_read_b128 v[194:197], v229 offset:20480
	ds_read_b128 v[198:201], v229 offset:24576
	ds_read_b128 v[202:205], v229 offset:28672
	s_waitcnt lgkmcnt(3)
	v_mfma_f32_32x32x16_bf16 v[114:129], v[186:189], v[190:193], v[114:129]
	s_add_u32 s10, s18, s10
	s_addc_u32 s11, s19, 0
	global_load_dwordx4 v[130:133], v226, s[10:11]
	s_add_u32 s10, s10, 0x10000
	s_addc_u32 s11, s11, 0
	s_waitcnt lgkmcnt(2)
	v_mfma_f32_32x32x16_bf16 v[82:97], v[186:189], v[194:197], v[82:97]
	s_waitcnt lgkmcnt(1)
	v_mfma_f32_32x32x16_bf16 v[50:65], v[186:189], v[198:201], v[50:65]
	global_load_dwordx4 v[138:141], v226, s[10:11]
	s_add_u32 s10, s10, 0x10000
	s_addc_u32 s11, s11, 0
	s_waitcnt lgkmcnt(0)
	v_mfma_f32_32x32x16_bf16 v[18:33], v[186:189], v[202:205], v[18:33]
	ds_read_b128 v[186:189], v228 offset:4096
	s_waitcnt lgkmcnt(0)
	v_mfma_f32_32x32x16_bf16 v[98:113], v[186:189], v[190:193], v[98:113]
	global_load_dwordx4 v[170:173], v226, s[10:11]
	s_add_u32 s10, s10, 0x10000
	s_addc_u32 s11, s11, 0
	v_mfma_f32_32x32x16_bf16 v[66:81], v[186:189], v[194:197], v[66:81]
	v_mfma_f32_32x32x16_bf16 v[34:49], v[186:189], v[198:201], v[34:49]
	global_load_dwordx4 v[134:137], v226, s[10:11]
	v_mfma_f32_32x32x16_bf16 v[2:17], v[186:189], v[202:205], v[2:17]
	ds_read_b128 v[186:189], v230
	ds_read_b128 v[190:193], v231 offset:16384
	ds_read_b128 v[194:197], v231 offset:20480
	ds_read_b128 v[198:201], v231 offset:24576
	ds_read_b128 v[202:205], v231 offset:28672
	s_waitcnt lgkmcnt(3)
	v_mfma_f32_32x32x16_bf16 v[114:129], v[186:189], v[190:193], v[114:129]
	s_lshl_b32 s10, s7, 7
	s_add_u32 s10, s22, s10
	s_addc_u32 s11, s23, 0
	global_load_dwordx4 v[174:177], v227, s[10:11]
	s_add_u32 s10, s10, 0x10000
	s_addc_u32 s11, s11, 0
	s_waitcnt lgkmcnt(2)
	v_mfma_f32_32x32x16_bf16 v[82:97], v[186:189], v[194:197], v[82:97]
	s_waitcnt lgkmcnt(1)
	v_mfma_f32_32x32x16_bf16 v[50:65], v[186:189], v[198:201], v[50:65]
	global_load_dwordx4 v[166:169], v227, s[10:11]
	s_add_u32 s10, s10, 0x10000
	s_addc_u32 s11, s11, 0
	s_waitcnt lgkmcnt(0)
	v_mfma_f32_32x32x16_bf16 v[18:33], v[186:189], v[202:205], v[18:33]
	ds_read_b128 v[186:189], v230 offset:4096
	s_waitcnt lgkmcnt(0)
	v_mfma_f32_32x32x16_bf16 v[98:113], v[186:189], v[190:193], v[98:113]
	global_load_dwordx4 v[162:165], v227, s[10:11]
	s_add_u32 s10, s10, 0x10000
	s_addc_u32 s11, s11, 0
	v_mfma_f32_32x32x16_bf16 v[66:81], v[186:189], v[194:197], v[66:81]
	v_mfma_f32_32x32x16_bf16 v[34:49], v[186:189], v[198:201], v[34:49]
	global_load_dwordx4 v[158:161], v227, s[10:11]
	s_add_u32 s10, s10, 0x10000
	s_addc_u32 s11, s11, 0
	v_mfma_f32_32x32x16_bf16 v[2:17], v[186:189], v[202:205], v[2:17]
	ds_read_b128 v[186:189], v232
	ds_read_b128 v[190:193], v233 offset:16384
	ds_read_b128 v[194:197], v233 offset:20480
	ds_read_b128 v[198:201], v233 offset:24576
	ds_read_b128 v[202:205], v233 offset:28672
	s_waitcnt lgkmcnt(3)
	v_mfma_f32_32x32x16_bf16 v[114:129], v[186:189], v[190:193], v[114:129]
	global_load_dwordx4 v[154:157], v227, s[10:11]
	s_add_u32 s10, s10, 0x10000
	s_addc_u32 s11, s11, 0
	s_waitcnt lgkmcnt(2)
	v_mfma_f32_32x32x16_bf16 v[82:97], v[186:189], v[194:197], v[82:97]
	s_waitcnt lgkmcnt(1)
	v_mfma_f32_32x32x16_bf16 v[50:65], v[186:189], v[198:201], v[50:65]
	global_load_dwordx4 v[150:153], v227, s[10:11]
	s_add_u32 s10, s10, 0x10000
	s_addc_u32 s11, s11, 0
	s_waitcnt lgkmcnt(0)
	v_mfma_f32_32x32x16_bf16 v[18:33], v[186:189], v[202:205], v[18:33]
	ds_read_b128 v[186:189], v232 offset:4096
	s_waitcnt lgkmcnt(0)
	v_mfma_f32_32x32x16_bf16 v[98:113], v[186:189], v[190:193], v[98:113]
	global_load_dwordx4 v[146:149], v227, s[10:11]
	s_add_u32 s10, s10, 0x10000
	s_addc_u32 s11, s11, 0
	v_mfma_f32_32x32x16_bf16 v[66:81], v[186:189], v[194:197], v[66:81]
	v_mfma_f32_32x32x16_bf16 v[34:49], v[186:189], v[198:201], v[34:49]
	global_load_dwordx4 v[142:145], v227, s[10:11]
	v_mfma_f32_32x32x16_bf16 v[2:17], v[186:189], v[202:205], v[2:17]
	ds_read_b128 v[186:189], v234
	ds_read_b128 v[190:193], v235 offset:16384
	ds_read_b128 v[194:197], v235 offset:20480
	ds_read_b128 v[198:201], v235 offset:24576
	ds_read_b128 v[202:205], v235 offset:28672
	s_waitcnt lgkmcnt(3)
	v_mfma_f32_32x32x16_bf16 v[114:129], v[186:189], v[190:193], v[114:129]
	s_waitcnt lgkmcnt(2)
	v_mfma_f32_32x32x16_bf16 v[82:97], v[186:189], v[194:197], v[82:97]
	s_waitcnt lgkmcnt(1)
	v_mfma_f32_32x32x16_bf16 v[50:65], v[186:189], v[198:201], v[50:65]
	s_waitcnt lgkmcnt(0)
	v_mfma_f32_32x32x16_bf16 v[18:33], v[186:189], v[202:205], v[18:33]
	ds_read_b128 v[186:189], v234 offset:4096
	s_waitcnt lgkmcnt(0)
	v_mfma_f32_32x32x16_bf16 v[98:113], v[186:189], v[190:193], v[98:113]
	v_mfma_f32_32x32x16_bf16 v[66:81], v[186:189], v[194:197], v[66:81]
	v_mfma_f32_32x32x16_bf16 v[34:49], v[186:189], v[198:201], v[34:49]
	v_mfma_f32_32x32x16_bf16 v[2:17], v[186:189], v[202:205], v[2:17]
	s_branch .Lkint_done_647

;     ...
;     for (int lt = lb; lt < per; lt += G8) {
;         const int grp = lt / (8 * nNt), q = lt - grp * 8 * nNt, gs = (mper - grp * 8) < 8 ? (mper - grp * 8) : 8;
;         const int tn = q / gs, tm = xcd * mper + grp * 8 + (q - tn * gs);
;         const bf16_t* Au = A + (size_t)(tm * 128) * lda;
;         const bf16_t* Bu = Bt + (size_t)(tn * 256) * ldb;
;         const unsigned voA = (unsigned)(lr * lda + lc * 8), voB = (unsigned)(lr * ldb + lc * 8);
;         f32x16 acc[2][4];
; #pragma unroll
;         for (int i = 0; i < 2; ++i)
; #pragma unroll
;             for (int j = 0; j < 4; ++j)
; #pragma unroll
;                 for (int r = 0; r < 16; ++r) acc[i][j][r] = 0.f;
;         u32x4 ra[4], rb[8];
; #pragma unroll
;         for (int i = 0; i < 4; ++i) ra[i] = *(const u32x4*)((Au + (size_t)(32 * i) * lda) + voA);
; #pragma unroll
;         for (int i = 0; i < 8; ++i) rb[i] = *(const u32x4*)((Bu + (size_t)(32 * i) * ldb) + voB);
;     ...
;                 const unsigned xo = (c0 ^ (unsigned)(2 * ks)) << 4;
; #pragma unroll
;                 for (int i = 0; i < 2; ++i) af[i] = *(const bf16x8*)(lds + (roA + xo) + i * 4096);
; #pragma unroll
;                 for (int j = 0; j < 4; ++j) bfr[j] = *(const bf16x8*)(lds + (roB + xo) + j * 4096);
.LBB0_733:
	s_mul_hi_i32 s4, s96, 0x2e8ba2e9
	s_lshr_b32 s6, s4, 31
	s_ashr_i32 s4, s4, 5
	s_add_i32 s4, s4, s6
	s_lshl_b32 s6, s4, 3
	s_sub_i32 s7, 0x42, s6
	s_min_u32 s7, s7, 8
	v_cvt_f32_ubyte0_e32 v1, s7
	v_rcp_iflag_f32_e32 v1, v1
	s_sub_i32 s10, 0, s7
	s_mulk_i32 s4, 0xff50
	s_add_i32 s4, s4, s96
	v_mul_f32_e32 v1, 0x4f7ffffe, v1
	v_cvt_u32_f32_e32 v1, v1
	s_abs_i32 s9, s4
	s_ashr_i32 s8, s4, 31
	v_mov_b32_e32 v14, v0
	v_readfirstlane_b32 s11, v1
	s_mul_i32 s10, s10, s11
	s_mul_hi_u32 s10, s11, s10
	s_add_i32 s11, s11, s10
	s_mul_hi_u32 s10, s9, s11
	s_mul_i32 s11, s10, s7
	s_sub_i32 s9, s9, s11
	s_add_i32 s11, s10, 1
	s_sub_i32 s18, s9, s7
	s_cmp_ge_u32 s9, s7
	s_cselect_b32 s10, s11, s10
	s_cselect_b32 s9, s18, s9
	s_add_i32 s11, s10, 1
	s_cmp_ge_u32 s9, s7
	s_cselect_b32 s9, s11, s10
	s_xor_b32 s9, s9, s8
	s_sub_i32 s8, s9, s8
	s_add_i32 s6, s6, s3
	s_mul_i32 s7, s7, s8
	s_add_i32 s6, s6, s4
	s_sub_i32 s4, s6, s7
	s_lshl_b32 s6, s4, 7
	s_ashr_i32 s7, s6, 31
	s_lshl_b64 s[18:19], s[6:7], 11
	v_lshl_add_u64 v[196:197], v[192:193], 0, s[18:19]
	v_add_co_u32_e32 v2, vcc, s14, v196
	s_lshl_b32 s8, s8, 8
	s_nop 0
	v_addc_co_u32_e32 v3, vcc, 0, v197, vcc
	v_add_co_u32_e32 v4, vcc, s15, v196
	s_ashr_i32 s9, s8, 31
	s_nop 0
	v_addc_co_u32_e32 v5, vcc, 0, v197, vcc
	s_lshl_b64 s[10:11], s[8:9], 11
	global_load_dwordx4 v[144:147], v[2:3], off
	global_load_dwordx4 v[152:155], v[4:5], off
	v_add_co_u32_e32 v2, vcc, s16, v196
	v_lshl_add_u64 v[198:199], v[194:195], 0, s[10:11]
	s_nop 0
	v_addc_co_u32_e32 v3, vcc, 0, v197, vcc
	v_add_co_u32_e32 v4, vcc, s14, v198
	global_load_dwordx4 v[148:151], v[196:197], off
	global_load_dwordx4 v[160:163], v[198:199], off
	v_addc_co_u32_e32 v5, vcc, 0, v199, vcc
	global_load_dwordx4 v[156:159], v[2:3], off
	global_load_dwordx4 v[164:167], v[4:5], off
	v_add_co_u32_e32 v2, vcc, s15, v198
	s_mov_b32 s4, 0x40000
	s_nop 0
	v_addc_co_u32_e32 v3, vcc, 0, v199, vcc
	v_add_co_u32_e32 v4, vcc, s16, v198
	v_mov_b32_e32 v15, v0
	s_nop 0
	v_addc_co_u32_e32 v5, vcc, 0, v199, vcc
	global_load_dwordx4 v[168:171], v[2:3], off
	global_load_dwordx4 v[172:175], v[4:5], off
	v_add_co_u32_e32 v2, vcc, s4, v198
	v_mov_b32_e32 v1, v0
	s_nop 0
	v_addc_co_u32_e32 v3, vcc, 0, v199, vcc
	v_add_co_u32_e32 v4, vcc, 0x50000, v198
	v_mov_b32_e32 v6, v0
	s_nop 0
	v_addc_co_u32_e32 v5, vcc, 0, v199, vcc
	global_load_dwordx4 v[176:179], v[2:3], off
	global_load_dwordx4 v[180:183], v[4:5], off
	v_add_co_u32_e32 v2, vcc, 0x60000, v198
	v_mov_b32_e32 v7, v0
	s_nop 0
	v_addc_co_u32_e32 v3, vcc, 0, v199, vcc
	v_add_co_u32_e32 v4, vcc, 0x70000, v198
	v_mov_b32_e32 v8, v0
	s_nop 0
	v_addc_co_u32_e32 v5, vcc, 0, v199, vcc
	global_load_dwordx4 v[184:187], v[2:3], off
	global_load_dwordx4 v[188:191], v[4:5], off
	v_mov_b32_e32 v2, v0
	v_mov_b32_e32 v3, v0
	v_mov_b32_e32 v4, v0
	v_mov_b32_e32 v5, v0
	v_mov_b32_e32 v9, v0
	v_mov_b32_e32 v10, v0
	v_mov_b32_e32 v11, v0
	v_mov_b32_e32 v12, v0
	v_mov_b32_e32 v13, v0
	v_mov_b64_e32 v[126:127], v[14:15]
	s_waitcnt vmcnt(20)
	v_mov_b64_e32 v[142:143], v[14:15]
	v_mov_b64_e32 v[62:63], v[14:15]
	v_mov_b64_e32 v[78:79], v[14:15]
	v_mov_b64_e32 v[94:95], v[14:15]
	v_mov_b64_e32 v[110:111], v[14:15]
	v_mov_b64_e32 v[30:31], v[14:15]
	v_mov_b64_e32 v[46:47], v[14:15]
	v_mov_b64_e32 v[124:125], v[12:13]
	v_mov_b64_e32 v[122:123], v[10:11]
	v_mov_b64_e32 v[120:121], v[8:9]
	v_mov_b64_e32 v[118:119], v[6:7]
	v_mov_b64_e32 v[116:117], v[4:5]
	v_mov_b64_e32 v[114:115], v[2:3]
	v_mov_b64_e32 v[112:113], v[0:1]
	v_mov_b64_e32 v[140:141], v[12:13]
	v_mov_b64_e32 v[138:139], v[10:11]
	v_mov_b64_e32 v[136:137], v[8:9]
	v_mov_b64_e32 v[134:135], v[6:7]
	v_mov_b64_e32 v[132:133], v[4:5]
	v_mov_b64_e32 v[130:131], v[2:3]
	v_mov_b64_e32 v[128:129], v[0:1]
	v_mov_b64_e32 v[60:61], v[12:13]
	v_mov_b64_e32 v[58:59], v[10:11]
	v_mov_b64_e32 v[56:57], v[8:9]
	v_mov_b64_e32 v[54:55], v[6:7]
	v_mov_b64_e32 v[52:53], v[4:5]
	v_mov_b64_e32 v[50:51], v[2:3]
	v_mov_b64_e32 v[48:49], v[0:1]
	v_mov_b64_e32 v[76:77], v[12:13]
	v_mov_b64_e32 v[74:75], v[10:11]
	v_mov_b64_e32 v[72:73], v[8:9]
	v_mov_b64_e32 v[70:71], v[6:7]
	v_mov_b64_e32 v[68:69], v[4:5]
	v_mov_b64_e32 v[66:67], v[2:3]
	v_mov_b64_e32 v[64:65], v[0:1]
	v_mov_b64_e32 v[92:93], v[12:13]
	v_mov_b64_e32 v[90:91], v[10:11]
	v_mov_b64_e32 v[88:89], v[8:9]
	v_mov_b64_e32 v[86:87], v[6:7]
	v_mov_b64_e32 v[84:85], v[4:5]
	v_mov_b64_e32 v[82:83], v[2:3]
	v_mov_b64_e32 v[80:81], v[0:1]
	v_mov_b64_e32 v[108:109], v[12:13]
	v_mov_b64_e32 v[106:107], v[10:11]
	v_mov_b64_e32 v[104:105], v[8:9]
	v_mov_b64_e32 v[102:103], v[6:7]
	v_mov_b64_e32 v[100:101], v[4:5]
	v_mov_b64_e32 v[98:99], v[2:3]
	v_mov_b64_e32 v[96:97], v[0:1]
	v_mov_b64_e32 v[28:29], v[12:13]
	v_mov_b64_e32 v[26:27], v[10:11]
	v_mov_b64_e32 v[24:25], v[8:9]
	v_mov_b64_e32 v[22:23], v[6:7]
	v_mov_b64_e32 v[20:21], v[4:5]
	v_mov_b64_e32 v[18:19], v[2:3]
	v_mov_b64_e32 v[16:17], v[0:1]
	v_mov_b64_e32 v[44:45], v[12:13]
	v_mov_b64_e32 v[42:43], v[10:11]
	v_mov_b64_e32 v[40:41], v[8:9]
	v_mov_b64_e32 v[38:39], v[6:7]
	v_mov_b64_e32 v[36:37], v[4:5]
	v_mov_b64_e32 v[34:35], v[2:3]
	v_mov_b64_e32 v[32:33], v[0:1]
	s_mov_b32 s7, s5
	v_readfirstlane_b32 s18, v196
	v_readfirstlane_b32 s19, v197
	v_readfirstlane_b32 s22, v198
	v_readfirstlane_b32 s23, v199
	v_subrev_u32_e32 v228, s18, v196
	v_subrev_u32_e32 v229, s22, v198
	v_xor_b32_e32 v231, 0, v201
	v_add_u32_e32 v230, v202, v231
	v_add_u32_e32 v231, v203, v231
	v_xor_b32_e32 v233, 32, v201
	v_add_u32_e32 v232, v202, v233
	v_add_u32_e32 v233, v203, v233
	v_xor_b32_e32 v235, 64, v201
	v_add_u32_e32 v234, v202, v235
	v_add_u32_e32 v235, v203, v235
	v_xor_b32_e32 v237, 0x60, v201
	v_add_u32_e32 v236, v202, v237
	v_add_u32_e32 v237, v203, v237
; DI unsigned swz(int row, int chunk) { return (unsigned)row * 128u + (unsigned)((chunk ^ ((row >> 1) & 7)) << 4); }
; #define MFMA32(a, b, c) __builtin_amdgcn_mfma_f32_32x32x16_bf16((a), (b), (c), 0, 0, 0)
;     ...
;         for (int kt = 0; kt < nk; ++kt) {
; #pragma unroll
;             for (int i = 0; i < 4; ++i) *(u32x4*)(lds + swz(lr + 32 * i, lc)) = ra[i];
; #pragma unroll
;             for (int i = 0; i < 8; ++i) *(u32x4*)(lds + 16384 + swz(lr + 32 * i, lc)) = rb[i];
;             __syncthreads();
;             if (kt + 1 < nk) {
; #pragma unroll
;                 for (int i = 0; i < 4; ++i) ra[i] = *(const u32x4*)((Au + (size_t)(32 * i) * lda + (kt + 1) * 64) + voA);
; #pragma unroll
;                 for (int i = 0; i < 8; ++i) rb[i] = *(const u32x4*)((Bu + (size_t)(32 * i) * ldb + (kt + 1) * 64) + voB);
;             }
;             __builtin_amdgcn_s_setprio(1);
; #pragma unroll 2
;             for (int ks = 0; ks < 4; ++ks) {
;                 bf16x8 af[2], bfr[4];
;                 const unsigned xo = (c0 ^ (unsigned)(2 * ks)) << 4;
; #pragma unroll
;                 for (int i = 0; i < 2; ++i) af[i] = *(const bf16x8*)(lds + (roA + xo) + i * 4096);
; #pragma unroll
;                 for (int j = 0; j < 4; ++j) bfr[j] = *(const bf16x8*)(lds + (roB + xo) + j * 4096);
; #pragma unroll
;                 for (int i = 0; i < 2; ++i)
; #pragma unroll
;                     for (int j = 0; j < 4; ++j) acc[i][j] = MFMA32(af[i], bfr[j], acc[i][j]);
;             }
;             __builtin_amdgcn_s_setprio(0);
;             __syncthreads();
.LBB0_734:
	s_mov_b32 s4, s7
	s_add_i32 s7, s7, 1
	s_cmp_lg_u32 s4, 15
	s_waitcnt vmcnt(9)
	ds_write_b128 v206, v[148:151]
	ds_write_b128 v206, v[144:147] offset:4096
	ds_write_b128 v206, v[152:155] offset:8192
	s_waitcnt vmcnt(7)
	ds_write_b128 v206, v[156:159] offset:12288
	ds_write_b128 v206, v[160:163] offset:16384
	s_waitcnt vmcnt(6)
	ds_write_b128 v206, v[164:167] offset:20480
	s_waitcnt vmcnt(5)
	ds_write_b128 v206, v[168:171] offset:24576
	s_waitcnt vmcnt(4)
	ds_write_b128 v206, v[172:175] offset:28672
	s_waitcnt vmcnt(3)
	ds_write_b128 v206, v[176:179] offset:32768
	s_waitcnt vmcnt(2)
	ds_write_b128 v206, v[180:183] offset:36864
	s_waitcnt vmcnt(1)
	ds_write_b128 v206, v[184:187] offset:40960
	s_waitcnt vmcnt(0)
	ds_write_b128 v206, v[188:191] offset:45056
	s_waitcnt lgkmcnt(0)
	s_barrier
	s_cbranch_scc0 .LBB0_736
	s_lshl_b32 s10, s7, 7
	s_setprio 1
	ds_read_b128 v[2:5], v230
	ds_read_b128 v[6:9], v231 offset:16384
	ds_read_b128 v[10:13], v230 offset:4096
	ds_read_b128 v[208:211], v231 offset:20480
	ds_read_b128 v[212:215], v231 offset:24576
	ds_read_b128 v[218:221], v231 offset:28672
	s_waitcnt lgkmcnt(4)
	v_mfma_f32_32x32x16_bf16 v[128:143], v[2:5], v[6:9], v[128:143]
	s_add_u32 s10, s18, s10
	s_addc_u32 s11, s19, 0
	global_load_dwordx4 v[148:151], v228, s[10:11]
	s_add_u32 s10, s10, 0x10000
	s_addc_u32 s11, s11, 0
	s_waitcnt lgkmcnt(2)
	v_mfma_f32_32x32x16_bf16 v[112:127], v[2:5], v[208:211], v[112:127]
	s_waitcnt lgkmcnt(1)
	v_mfma_f32_32x32x16_bf16 v[48:63], v[2:5], v[212:215], v[48:63]
	global_load_dwordx4 v[144:147], v228, s[10:11]
	s_add_u32 s10, s10, 0x10000
	s_addc_u32 s11, s11, 0
	s_waitcnt lgkmcnt(0)
	v_mfma_f32_32x32x16_bf16 v[64:79], v[2:5], v[218:221], v[64:79]
	v_mfma_f32_32x32x16_bf16 v[80:95], v[10:13], v[6:9], v[80:95]
	global_load_dwordx4 v[152:155], v228, s[10:11]
	s_add_u32 s10, s10, 0x10000
	s_addc_u32 s11, s11, 0
	v_mfma_f32_32x32x16_bf16 v[96:111], v[10:13], v[208:211], v[96:111]
	v_mfma_f32_32x32x16_bf16 v[16:31], v[10:13], v[212:215], v[16:31]
	global_load_dwordx4 v[156:159], v228, s[10:11]
	v_mfma_f32_32x32x16_bf16 v[32:47], v[10:13], v[218:221], v[32:47]
	ds_read_b128 v[2:5], v232
	ds_read_b128 v[6:9], v233 offset:16384
	ds_read_b128 v[10:13], v232 offset:4096
	ds_read_b128 v[208:211], v233 offset:20480
	ds_read_b128 v[212:215], v233 offset:24576
	ds_read_b128 v[218:221], v233 offset:28672
	s_waitcnt lgkmcnt(4)
	v_mfma_f32_32x32x16_bf16 v[128:143], v[2:5], v[6:9], v[128:143]
	s_lshl_b32 s10, s7, 7
	s_add_u32 s10, s22, s10
	s_addc_u32 s11, s23, 0
	global_load_dwordx4 v[160:163], v229, s[10:11]
	s_add_u32 s10, s10, 0x10000
	s_addc_u32 s11, s11, 0
	s_waitcnt lgkmcnt(2)
	v_mfma_f32_32x32x16_bf16 v[112:127], v[2:5], v[208:211], v[112:127]
	s_waitcnt lgkmcnt(1)
	v_mfma_f32_32x32x16_bf16 v[48:63], v[2:5], v[212:215], v[48:63]
	global_load_dwordx4 v[164:167], v229, s[10:11]
	s_add_u32 s10, s10, 0x10000
	s_addc_u32 s11, s11, 0
	s_waitcnt lgkmcnt(0)
	v_mfma_f32_32x32x16_bf16 v[64:79], v[2:5], v[218:221], v[64:79]
	v_mfma_f32_32x32x16_bf16 v[80:95], v[10:13], v[6:9], v[80:95]
	global_load_dwordx4 v[168:171], v229, s[10:11]
	s_add_u32 s10, s10, 0x10000
	s_addc_u32 s11, s11, 0
	v_mfma_f32_32x32x16_bf16 v[96:111], v[10:13], v[208:211], v[96:111]
	v_mfma_f32_32x32x16_bf16 v[16:31], v[10:13], v[212:215], v[16:31]
	global_load_dwordx4 v[172:175], v229, s[10:11]
	s_add_u32 s10, s10, 0x10000
	s_addc_u32 s11, s11, 0
	v_mfma_f32_32x32x16_bf16 v[32:47], v[10:13], v[218:221], v[32:47]
	ds_read_b128 v[2:5], v234
	ds_read_b128 v[6:9], v235 offset:16384
	ds_read_b128 v[10:13], v234 offset:4096
	ds_read_b128 v[208:211], v235 offset:20480
	ds_read_b128 v[212:215], v235 offset:24576
	ds_read_b128 v[218:221], v235 offset:28672
	s_waitcnt lgkmcnt(4)
	v_mfma_f32_32x32x16_bf16 v[128:143], v[2:5], v[6:9], v[128:143]
	global_load_dwordx4 v[176:179], v229, s[10:11]
	s_add_u32 s10, s10, 0x10000
	s_addc_u32 s11, s11, 0
	s_waitcnt lgkmcnt(2)
	v_mfma_f32_32x32x16_bf16 v[112:127], v[2:5], v[208:211], v[112:127]
	s_waitcnt lgkmcnt(1)
	v_mfma_f32_32x32x16_bf16 v[48:63], v[2:5], v[212:215], v[48:63]
	global_load_dwordx4 v[180:183], v229, s[10:11]
	s_add_u32 s10, s10, 0x10000
	s_addc_u32 s11, s11, 0
	s_waitcnt lgkmcnt(0)
	v_mfma_f32_32x32x16_bf16 v[64:79], v[2:5], v[218:221], v[64:79]
	v_mfma_f32_32x32x16_bf16 v[80:95], v[10:13], v[6:9], v[80:95]
	global_load_dwordx4 v[184:187], v229, s[10:11]
	s_add_u32 s10, s10, 0x10000
	s_addc_u32 s11, s11, 0
	v_mfma_f32_32x32x16_bf16 v[96:111], v[10:13], v[208:211], v[96:111]
	v_mfma_f32_32x32x16_bf16 v[16:31], v[10:13], v[212:215], v[16:31]
	global_load_dwordx4 v[188:191], v229, s[10:11]
	v_mfma_f32_32x32x16_bf16 v[32:47], v[10:13], v[218:221], v[32:47]
	ds_read_b128 v[2:5], v236
	ds_read_b128 v[6:9], v237 offset:16384
	ds_read_b128 v[10:13], v236 offset:4096
	ds_read_b128 v[208:211], v237 offset:20480
	ds_read_b128 v[212:215], v237 offset:24576
	ds_read_b128 v[218:221], v237 offset:28672
	s_waitcnt lgkmcnt(4)
	v_mfma_f32_32x32x16_bf16 v[128:143], v[2:5], v[6:9], v[128:143]
	s_waitcnt lgkmcnt(2)
	v_mfma_f32_32x32x16_bf16 v[112:127], v[2:5], v[208:211], v[112:127]
	s_waitcnt lgkmcnt(1)
	v_mfma_f32_32x32x16_bf16 v[48:63], v[2:5], v[212:215], v[48:63]
	s_waitcnt lgkmcnt(0)
	v_mfma_f32_32x32x16_bf16 v[64:79], v[2:5], v[218:221], v[64:79]
	v_mfma_f32_32x32x16_bf16 v[80:95], v[10:13], v[6:9], v[80:95]
	v_mfma_f32_32x32x16_bf16 v[96:111], v[10:13], v[208:211], v[96:111]
	v_mfma_f32_32x32x16_bf16 v[16:31], v[10:13], v[212:215], v[16:31]
	v_mfma_f32_32x32x16_bf16 v[32:47], v[10:13], v[218:221], v[32:47]
	s_branch .Lkint_done_737

;     ...
;     for (int lt = lb; lt < per; lt += G8) {
;         const int grp = lt / (8 * nNt), q = lt - grp * 8 * nNt, gs = (mper - grp * 8) < 8 ? (mper - grp * 8) : 8;
;         const int tn = q / gs, tm = xcd * mper + grp * 8 + (q - tn * gs);
;         const bf16_t* Au = A + (size_t)(tm * 128) * lda;
;         const bf16_t* Bu = Bt + (size_t)(tn * 256) * ldb;
;         const unsigned voA = (unsigned)(lr * lda + lc * 8), voB = (unsigned)(lr * ldb + lc * 8);
;         f32x16 acc[2][4];
; #pragma unroll
;         for (int i = 0; i < 2; ++i)
; #pragma unroll
;             for (int j = 0; j < 4; ++j)
; #pragma unroll
;                 for (int r = 0; r < 16; ++r) acc[i][j][r] = 0.f;
;         u32x4 ra[4], rb[8];
; #pragma unroll
;         for (int i = 0; i < 4; ++i) ra[i] = *(const u32x4*)((Au + (size_t)(32 * i) * lda) + voA);
; #pragma unroll
;         for (int i = 0; i < 8; ++i) rb[i] = *(const u32x4*)((Bu + (size_t)(32 * i) * ldb) + voB);
;     ...
;                 const unsigned xo = (c0 ^ (unsigned)(2 * ks)) << 4;
; #pragma unroll
;                 for (int i = 0; i < 2; ++i) af[i] = *(const bf16x8*)(lds + (roA + xo) + i * 4096);
; #pragma unroll
;                 for (int j = 0; j < 4; ++j) bfr[j] = *(const bf16x8*)(lds + (roB + xo) + j * 4096);
.LBB0_779:
	s_ashr_i32 s0, s92, 31
	s_lshr_b32 s0, s0, 27
	s_add_i32 s0, s92, s0
	s_ashr_i32 s10, s0, 5
	s_lshl_b32 s10, s10, 3
	s_sub_i32 s11, 0x42, s10
	s_min_u32 s11, s11, 8
	v_cvt_f32_ubyte0_e32 v1, s11
	v_rcp_iflag_f32_e32 v1, v1
	s_sub_i32 s80, 0, s11
	s_andn2_b32 s0, s0, 31
	s_sub_i32 s0, s92, s0
	v_mul_f32_e32 v1, 0x4f7ffffe, v1
	v_cvt_u32_f32_e32 v1, v1
	s_abs_i32 s19, s0
	s_ashr_i32 s18, s0, 31
	v_mov_b32_e32 v14, v0
	v_readfirstlane_b32 s93, v1
	s_mul_i32 s80, s80, s93
	s_mul_hi_u32 s80, s93, s80
	s_add_i32 s93, s93, s80
	s_mul_hi_u32 s80, s19, s93
	s_mul_i32 s93, s80, s11
	s_sub_i32 s19, s19, s93
	s_add_i32 s94, s80, 1
	s_sub_i32 s93, s19, s11
	s_cmp_ge_u32 s19, s11
	s_cselect_b32 s80, s94, s80
	s_cselect_b32 s19, s93, s19
	s_add_i32 s93, s80, 1
	s_cmp_ge_u32 s19, s11
	s_cselect_b32 s19, s93, s80
	s_xor_b32 s19, s19, s18
	s_sub_i32 s18, s19, s18
	s_add_i32 s10, s10, s3
	s_mul_i32 s11, s11, s18
	s_add_i32 s10, s10, s0
	s_sub_i32 s0, s10, s11
	s_lshl_b32 s93, s18, 8
	s_lshl_b32 s80, s0, 7
	v_mad_i64_i32 v[184:185], s[10:11], s93, v192, v[180:181]
	s_mov_b32 s0, 0x134000
	v_add_co_u32_e32 v2, vcc, s0, v184
	s_mov_b32 s0, 0x108000
	s_nop 0
	v_addc_co_u32_e32 v3, vcc, 0, v185, vcc
	v_add_co_u32_e32 v4, vcc, s0, v184
	s_mov_b32 s0, 0xdc000
	s_nop 0
	v_addc_co_u32_e32 v5, vcc, 0, v185, vcc
	global_load_dwordx4 v[142:145], v[2:3], off
	global_load_dwordx4 v[146:149], v[4:5], off
	v_add_co_u32_e32 v2, vcc, s0, v184
	s_mov_b32 s0, 0xb0000
	s_nop 0
	v_addc_co_u32_e32 v3, vcc, 0, v185, vcc
	v_add_co_u32_e32 v4, vcc, s0, v184
	v_mad_i64_i32 v[182:183], s[10:11], s80, v192, v[178:179]
	s_nop 0
	v_addc_co_u32_e32 v5, vcc, 0, v185, vcc
	global_load_dwordx4 v[150:153], v[2:3], off
	global_load_dwordx4 v[154:157], v[4:5], off
	v_add_co_u32_e32 v2, vcc, s6, v184
	v_mov_b32_e32 v15, v0
	s_nop 0
	v_addc_co_u32_e32 v3, vcc, 0, v185, vcc
	v_add_co_u32_e32 v4, vcc, 0x58000, v184
	v_mov_b32_e32 v1, v0
	s_nop 0
	v_addc_co_u32_e32 v5, vcc, 0, v185, vcc
	global_load_dwordx4 v[158:161], v[2:3], off
	global_load_dwordx4 v[162:165], v[4:5], off
	v_add_co_u32_e32 v2, vcc, 0x2c000, v184
	v_mov_b32_e32 v6, v0
	s_nop 0
	v_addc_co_u32_e32 v3, vcc, 0, v185, vcc
	v_add_co_u32_e32 v4, vcc, 0x84000, v182
	v_mov_b32_e32 v7, v0
	s_nop 0
	v_addc_co_u32_e32 v5, vcc, 0, v183, vcc
	global_load_dwordx4 v[166:169], v[2:3], off
	global_load_dwordx4 v[134:137], v[4:5], off
	v_add_co_u32_e32 v2, vcc, 0x58000, v182
	v_mov_b32_e32 v8, v0
	s_nop 0
	v_addc_co_u32_e32 v3, vcc, 0, v183, vcc
	v_add_co_u32_e32 v4, vcc, 0x2c000, v182
	v_mov_b32_e32 v9, v0
	s_nop 0
	v_addc_co_u32_e32 v5, vcc, 0, v183, vcc
	global_load_dwordx4 v[170:173], v[2:3], off
	global_load_dwordx4 v[138:141], v[4:5], off
	global_load_dwordx4 v[174:177], v[184:185], off
	global_load_dwordx4 v[130:133], v[182:183], off
	v_mov_b32_e32 v2, v0
	v_mov_b32_e32 v3, v0
	v_mov_b32_e32 v4, v0
	v_mov_b32_e32 v5, v0
	v_mov_b32_e32 v10, v0
	v_mov_b32_e32 v11, v0
	v_mov_b32_e32 v12, v0
	v_mov_b32_e32 v13, v0
	s_waitcnt vmcnt(20)
	v_mov_b64_e32 v[96:97], v[14:15]
	v_mov_b64_e32 v[128:129], v[14:15]
	v_mov_b64_e32 v[64:65], v[14:15]
	v_mov_b64_e32 v[32:33], v[14:15]
	v_mov_b64_e32 v[112:113], v[14:15]
	v_mov_b64_e32 v[80:81], v[14:15]
	v_mov_b64_e32 v[48:49], v[14:15]
	v_mov_b64_e32 v[94:95], v[12:13]
	v_mov_b64_e32 v[92:93], v[10:11]
	v_mov_b64_e32 v[90:91], v[8:9]
	v_mov_b64_e32 v[88:89], v[6:7]
	v_mov_b64_e32 v[86:87], v[4:5]
	v_mov_b64_e32 v[84:85], v[2:3]
	v_mov_b64_e32 v[82:83], v[0:1]
	v_mov_b64_e32 v[126:127], v[12:13]
	v_mov_b64_e32 v[124:125], v[10:11]
	v_mov_b64_e32 v[122:123], v[8:9]
	v_mov_b64_e32 v[120:121], v[6:7]
	v_mov_b64_e32 v[118:119], v[4:5]
	v_mov_b64_e32 v[116:117], v[2:3]
	v_mov_b64_e32 v[114:115], v[0:1]
	v_mov_b64_e32 v[62:63], v[12:13]
	v_mov_b64_e32 v[60:61], v[10:11]
	v_mov_b64_e32 v[58:59], v[8:9]
	v_mov_b64_e32 v[56:57], v[6:7]
	v_mov_b64_e32 v[54:55], v[4:5]
	v_mov_b64_e32 v[52:53], v[2:3]
	v_mov_b64_e32 v[50:51], v[0:1]
	v_mov_b64_e32 v[30:31], v[12:13]
	v_mov_b64_e32 v[28:29], v[10:11]
	v_mov_b64_e32 v[26:27], v[8:9]
	v_mov_b64_e32 v[24:25], v[6:7]
	v_mov_b64_e32 v[22:23], v[4:5]
	v_mov_b64_e32 v[20:21], v[2:3]
	v_mov_b64_e32 v[18:19], v[0:1]
	v_mov_b64_e32 v[110:111], v[12:13]
	v_mov_b64_e32 v[108:109], v[10:11]
	v_mov_b64_e32 v[106:107], v[8:9]
	v_mov_b64_e32 v[104:105], v[6:7]
	v_mov_b64_e32 v[102:103], v[4:5]
	v_mov_b64_e32 v[100:101], v[2:3]
	v_mov_b64_e32 v[98:99], v[0:1]
	v_mov_b64_e32 v[78:79], v[12:13]
	v_mov_b64_e32 v[76:77], v[10:11]
	v_mov_b64_e32 v[74:75], v[8:9]
	v_mov_b64_e32 v[72:73], v[6:7]
	v_mov_b64_e32 v[70:71], v[4:5]
	v_mov_b64_e32 v[68:69], v[2:3]
	v_mov_b64_e32 v[66:67], v[0:1]
	v_mov_b64_e32 v[46:47], v[12:13]
	v_mov_b64_e32 v[44:45], v[10:11]
	v_mov_b64_e32 v[42:43], v[8:9]
	v_mov_b64_e32 v[40:41], v[6:7]
	v_mov_b64_e32 v[38:39], v[4:5]
	v_mov_b64_e32 v[36:37], v[2:3]
	v_mov_b64_e32 v[34:35], v[0:1]
	v_mov_b64_e32 v[16:17], v[14:15]
	v_mov_b64_e32 v[14:15], v[12:13]
	v_mov_b64_e32 v[12:13], v[10:11]
	v_mov_b64_e32 v[10:11], v[8:9]
	v_mov_b64_e32 v[8:9], v[6:7]
	v_mov_b64_e32 v[6:7], v[4:5]
	v_mov_b64_e32 v[4:5], v[2:3]
	v_mov_b64_e32 v[2:3], v[0:1]
	s_mov_b32 s94, s1
	v_readfirstlane_b32 s22, v182
	v_readfirstlane_b32 s23, v183
	v_readfirstlane_b32 s52, v184
	v_readfirstlane_b32 s53, v185
	v_subrev_u32_e32 v228, s22, v182
	v_subrev_u32_e32 v229, s52, v184
	v_xor_b32_e32 v231, 0, v187
	v_add_u32_e32 v230, v188, v231
	v_add_u32_e32 v231, v189, v231
	v_xor_b32_e32 v233, 32, v187
	v_add_u32_e32 v232, v188, v233
	v_add_u32_e32 v233, v189, v233
	v_xor_b32_e32 v235, 64, v187
	v_add_u32_e32 v234, v188, v235
	v_add_u32_e32 v235, v189, v235
	v_xor_b32_e32 v237, 0x60, v187
	v_add_u32_e32 v236, v188, v237
	v_add_u32_e32 v237, v189, v237
; DI unsigned swz(int row, int chunk) { return (unsigned)row * 128u + (unsigned)((chunk ^ ((row >> 1) & 7)) << 4); }
; #define MFMA32(a, b, c) __builtin_amdgcn_mfma_f32_32x32x16_bf16((a), (b), (c), 0, 0, 0)
;     ...
;         for (int kt = 0; kt < nk; ++kt) {
; #pragma unroll
;             for (int i = 0; i < 4; ++i) *(u32x4*)(lds + swz(lr + 32 * i, lc)) = ra[i];
; #pragma unroll
;             for (int i = 0; i < 8; ++i) *(u32x4*)(lds + 16384 + swz(lr + 32 * i, lc)) = rb[i];
;             __syncthreads();
;             if (kt + 1 < nk) {
; #pragma unroll
;                 for (int i = 0; i < 4; ++i) ra[i] = *(const u32x4*)((Au + (size_t)(32 * i) * lda + (kt + 1) * 64) + voA);
; #pragma unroll
;                 for (int i = 0; i < 8; ++i) rb[i] = *(const u32x4*)((Bu + (size_t)(32 * i) * ldb + (kt + 1) * 64) + voB);
;             }
;             __builtin_amdgcn_s_setprio(1);
; #pragma unroll 2
;             for (int ks = 0; ks < 4; ++ks) {
;                 bf16x8 af[2], bfr[4];
;                 const unsigned xo = (c0 ^ (unsigned)(2 * ks)) << 4;
; #pragma unroll
;                 for (int i = 0; i < 2; ++i) af[i] = *(const bf16x8*)(lds + (roA + xo) + i * 4096);
; #pragma unroll
;                 for (int j = 0; j < 4; ++j) bfr[j] = *(const bf16x8*)(lds + (roB + xo) + j * 4096);
; #pragma unroll
;                 for (int i = 0; i < 2; ++i)
; #pragma unroll
;                     for (int j = 0; j < 4; ++j) acc[i][j] = MFMA32(af[i], bfr[j], acc[i][j]);
;             }
;             __builtin_amdgcn_s_setprio(0);
;             __syncthreads();
.LBB0_780:
	s_mov_b32 s0, s94
	s_add_i32 s94, s94, 1
	s_cmp_lt_u32 s0, 43
	s_waitcnt vmcnt(0)
	ds_write_b128 v193, v[130:133]
	ds_write_b128 v193, v[138:141] offset:4096
	ds_write_b128 v193, v[170:173] offset:8192
	ds_write_b128 v193, v[134:137] offset:12288
	ds_write_b128 v193, v[174:177] offset:16384
	ds_write_b128 v193, v[166:169] offset:20480
	ds_write_b128 v193, v[162:165] offset:24576
	ds_write_b128 v193, v[158:161] offset:28672
	ds_write_b128 v193, v[154:157] offset:32768
	ds_write_b128 v193, v[150:153] offset:36864
	ds_write_b128 v193, v[146:149] offset:40960
	ds_write_b128 v193, v[142:145] offset:45056
	s_waitcnt lgkmcnt(0)
	s_barrier
	s_cbranch_scc0 .LBB0_782
	s_lshl_b32 s18, s94, 7
	s_setprio 1
	ds_read_b128 v[194:197], v230
	ds_read_b128 v[198:201], v231 offset:16384
	ds_read_b128 v[202:205], v230 offset:4096
	ds_read_b128 v[206:209], v231 offset:20480
	ds_read_b128 v[210:213], v231 offset:24576
	ds_read_b128 v[218:221], v231 offset:28672
	s_waitcnt lgkmcnt(4)
	v_mfma_f32_32x32x16_bf16 v[114:129], v[194:197], v[198:201], v[114:129]
	s_add_u32 s18, s22, s18
	s_addc_u32 s19, s23, 0
	global_load_dwordx4 v[130:133], v228, s[18:19]
	s_add_u32 s18, s18, 0x2c000
	s_addc_u32 s19, s19, 0
	s_waitcnt lgkmcnt(2)
	v_mfma_f32_32x32x16_bf16 v[82:97], v[194:197], v[206:209], v[82:97]
	s_waitcnt lgkmcnt(1)
	v_mfma_f32_32x32x16_bf16 v[50:65], v[194:197], v[210:213], v[50:65]
	global_load_dwordx4 v[138:141], v228, s[18:19]
	s_add_u32 s18, s18, 0x2c000
	s_addc_u32 s19, s19, 0
	s_waitcnt lgkmcnt(0)
	v_mfma_f32_32x32x16_bf16 v[18:33], v[194:197], v[218:221], v[18:33]
	v_mfma_f32_32x32x16_bf16 v[98:113], v[202:205], v[198:201], v[98:113]
	global_load_dwordx4 v[170:173], v228, s[18:19]
	s_add_u32 s18, s18, 0x2c000
	s_addc_u32 s19, s19, 0
	v_mfma_f32_32x32x16_bf16 v[66:81], v[202:205], v[206:209], v[66:81]
	v_mfma_f32_32x32x16_bf16 v[34:49], v[202:205], v[210:213], v[34:49]
	global_load_dwordx4 v[134:137], v228, s[18:19]
	v_mfma_f32_32x32x16_bf16 v[2:17], v[202:205], v[218:221], v[2:17]
	ds_read_b128 v[194:197], v232
	ds_read_b128 v[198:201], v233 offset:16384
	ds_read_b128 v[202:205], v232 offset:4096
	ds_read_b128 v[206:209], v233 offset:20480
	ds_read_b128 v[210:213], v233 offset:24576
	ds_read_b128 v[218:221], v233 offset:28672
	s_waitcnt lgkmcnt(4)
	v_mfma_f32_32x32x16_bf16 v[114:129], v[194:197], v[198:201], v[114:129]
	s_lshl_b32 s18, s94, 7
	s_add_u32 s18, s52, s18
	s_addc_u32 s19, s53, 0
	global_load_dwordx4 v[174:177], v229, s[18:19]
	s_add_u32 s18, s18, 0x2c000
	s_addc_u32 s19, s19, 0
	s_waitcnt lgkmcnt(2)
	v_mfma_f32_32x32x16_bf16 v[82:97], v[194:197], v[206:209], v[82:97]
	s_waitcnt lgkmcnt(1)
	v_mfma_f32_32x32x16_bf16 v[50:65], v[194:197], v[210:213], v[50:65]
	global_load_dwordx4 v[166:169], v229, s[18:19]
	s_add_u32 s18, s18, 0x2c000
	s_addc_u32 s19, s19, 0
	s_waitcnt lgkmcnt(0)
	v_mfma_f32_32x32x16_bf16 v[18:33], v[194:197], v[218:221], v[18:33]
	v_mfma_f32_32x32x16_bf16 v[98:113], v[202:205], v[198:201], v[98:113]
	global_load_dwordx4 v[162:165], v229, s[18:19]
	s_add_u32 s18, s18, 0x2c000
	s_addc_u32 s19, s19, 0
	v_mfma_f32_32x32x16_bf16 v[66:81], v[202:205], v[206:209], v[66:81]
	v_mfma_f32_32x32x16_bf16 v[34:49], v[202:205], v[210:213], v[34:49]
	global_load_dwordx4 v[158:161], v229, s[18:19]
	s_add_u32 s18, s18, 0x2c000
	s_addc_u32 s19, s19, 0
	v_mfma_f32_32x32x16_bf16 v[2:17], v[202:205], v[218:221], v[2:17]
	ds_read_b128 v[194:197], v234
	ds_read_b128 v[198:201], v235 offset:16384
	ds_read_b128 v[202:205], v234 offset:4096
	ds_read_b128 v[206:209], v235 offset:20480
	ds_read_b128 v[210:213], v235 offset:24576
	ds_read_b128 v[218:221], v235 offset:28672
	s_waitcnt lgkmcnt(4)
	v_mfma_f32_32x32x16_bf16 v[114:129], v[194:197], v[198:201], v[114:129]
	global_load_dwordx4 v[154:157], v229, s[18:19]
	s_add_u32 s18, s18, 0x2c000
	s_addc_u32 s19, s19, 0
	s_waitcnt lgkmcnt(2)
	v_mfma_f32_32x32x16_bf16 v[82:97], v[194:197], v[206:209], v[82:97]
	s_waitcnt lgkmcnt(1)
	v_mfma_f32_32x32x16_bf16 v[50:65], v[194:197], v[210:213], v[50:65]
	global_load_dwordx4 v[150:153], v229, s[18:19]
	s_add_u32 s18, s18, 0x2c000
	s_addc_u32 s19, s19, 0
	s_waitcnt lgkmcnt(0)
	v_mfma_f32_32x32x16_bf16 v[18:33], v[194:197], v[218:221], v[18:33]
	v_mfma_f32_32x32x16_bf16 v[98:113], v[202:205], v[198:201], v[98:113]
	global_load_dwordx4 v[146:149], v229, s[18:19]
	s_add_u32 s18, s18, 0x2c000
	s_addc_u32 s19, s19, 0
	v_mfma_f32_32x32x16_bf16 v[66:81], v[202:205], v[206:209], v[66:81]
	v_mfma_f32_32x32x16_bf16 v[34:49], v[202:205], v[210:213], v[34:49]
	global_load_dwordx4 v[142:145], v229, s[18:19]
	v_mfma_f32_32x32x16_bf16 v[2:17], v[202:205], v[218:221], v[2:17]
	ds_read_b128 v[194:197], v236
	ds_read_b128 v[198:201], v237 offset:16384
	ds_read_b128 v[202:205], v236 offset:4096
	ds_read_b128 v[206:209], v237 offset:20480
	ds_read_b128 v[210:213], v237 offset:24576
	ds_read_b128 v[218:221], v237 offset:28672
	s_waitcnt lgkmcnt(4)
	v_mfma_f32_32x32x16_bf16 v[114:129], v[194:197], v[198:201], v[114:129]
	s_waitcnt lgkmcnt(2)
	v_mfma_f32_32x32x16_bf16 v[82:97], v[194:197], v[206:209], v[82:97]
	s_waitcnt lgkmcnt(1)
	v_mfma_f32_32x32x16_bf16 v[50:65], v[194:197], v[210:213], v[50:65]
	s_waitcnt lgkmcnt(0)
	v_mfma_f32_32x32x16_bf16 v[18:33], v[194:197], v[218:221], v[18:33]
	v_mfma_f32_32x32x16_bf16 v[98:113], v[202:205], v[198:201], v[98:113]
	v_mfma_f32_32x32x16_bf16 v[66:81], v[202:205], v[206:209], v[66:81]
	v_mfma_f32_32x32x16_bf16 v[34:49], v[202:205], v[210:213], v[34:49]
	v_mfma_f32_32x32x16_bf16 v[2:17], v[202:205], v[218:221], v[2:17]
	s_branch .Lkint_done_783

;     ...
;     for (int lt = lb; lt < per; lt += G8) {
;         const int grp = lt / (8 * nNt), q = lt - grp * 8 * nNt, gs = (mper - grp * 8) < 8 ? (mper - grp * 8) : 8;
;         const int tn = q / gs, tm = xcd * mper + grp * 8 + (q - tn * gs);
;         const bf16_t* Au = A + (size_t)(tm * 128) * lda;
;         const bf16_t* Bu = Bt + (size_t)(tn * 256) * ldb;
;         const unsigned voA = (unsigned)(lr * lda + lc * 8), voB = (unsigned)(lr * ldb + lc * 8);
;         f32x16 acc[2][4];
; #pragma unroll
;         for (int i = 0; i < 2; ++i)
; #pragma unroll
;             for (int j = 0; j < 4; ++j)
; #pragma unroll
;                 for (int r = 0; r < 16; ++r) acc[i][j][r] = 0.f;
;         u32x4 ra[4], rb[8];
; #pragma unroll
;         for (int i = 0; i < 4; ++i) ra[i] = *(const u32x4*)((Au + (size_t)(32 * i) * lda) + voA);
; #pragma unroll
;         for (int i = 0; i < 8; ++i) rb[i] = *(const u32x4*)((Bu + (size_t)(32 * i) * ldb) + voB);
;     ...
;                 const unsigned xo = (c0 ^ (unsigned)(2 * ks)) << 4;
; #pragma unroll
;                 for (int i = 0; i < 2; ++i) af[i] = *(const bf16x8*)(lds + (roA + xo) + i * 4096);
; #pragma unroll
;                 for (int j = 0; j < 4; ++j) bfr[j] = *(const bf16x8*)(lds + (roB + xo) + j * 4096);
.LBB0_870:
	s_mul_hi_i32 s0, s96, 0x2aaaaaab
	s_lshr_b32 s4, s0, 31
	s_ashr_i32 s0, s0, 4
	s_add_i32 s0, s0, s4
	s_lshl_b32 s4, s0, 3
	s_sub_i32 s5, 0x42, s4
	s_min_u32 s5, s5, 8
	v_cvt_f32_ubyte0_e32 v1, s5
	v_rcp_iflag_f32_e32 v1, v1
	s_sub_i32 s10, 0, s5
	s_mulk_i32 s0, 0xffa0
	s_add_i32 s0, s0, s96
	v_mul_f32_e32 v1, 0x4f7ffffe, v1
	v_cvt_u32_f32_e32 v1, v1
	s_abs_i32 s7, s0
	s_ashr_i32 s6, s0, 31
	v_mov_b32_e32 v14, v0
	v_readfirstlane_b32 s11, v1
	s_mul_i32 s10, s10, s11
	s_mul_hi_u32 s10, s11, s10
	s_add_i32 s11, s11, s10
	s_mul_hi_u32 s10, s7, s11
	s_mul_i32 s11, s10, s5
	s_sub_i32 s7, s7, s11
	s_add_i32 s11, s10, 1
	s_sub_i32 s18, s7, s5
	s_cmp_ge_u32 s7, s5
	s_cselect_b32 s10, s11, s10
	s_cselect_b32 s7, s18, s7
	s_add_i32 s11, s10, 1
	s_cmp_ge_u32 s7, s5
	s_cselect_b32 s7, s11, s10
	s_xor_b32 s7, s7, s6
	s_sub_i32 s10, s7, s6
	s_add_i32 s4, s4, s3
	s_mul_i32 s5, s5, s10
	s_add_i32 s4, s4, s0
	s_sub_i32 s0, s4, s5
	s_lshl_b32 s6, s0, 7
	s_ashr_i32 s7, s6, 31
	s_lshl_b32 s4, s10, 8
	s_ashr_i32 s5, s4, 31
	s_lshl_b64 s[10:11], s[6:7], 11
	v_lshl_add_u64 v[182:183], v[178:179], 0, s[10:11]
	s_lshl_b64 s[10:11], s[4:5], 11
	v_lshl_add_u64 v[184:185], v[180:181], 0, s[10:11]
	v_add_co_u32_e32 v2, vcc, s8, v184
	v_mov_b32_e32 v15, v0
	s_nop 0
	v_addc_co_u32_e32 v3, vcc, 0, v185, vcc
	v_add_co_u32_e32 v4, vcc, s9, v184
	v_mov_b32_e32 v1, v0
	s_nop 0
	v_addc_co_u32_e32 v5, vcc, 0, v185, vcc
	global_load_dwordx4 v[142:145], v[2:3], off
	global_load_dwordx4 v[146:149], v[4:5], off
	v_add_co_u32_e32 v2, vcc, s12, v184
	v_mov_b32_e32 v6, v0
	s_nop 0
	v_addc_co_u32_e32 v3, vcc, 0, v185, vcc
	v_add_co_u32_e32 v4, vcc, s13, v184
	v_mov_b32_e32 v7, v0
	s_nop 0
	v_addc_co_u32_e32 v5, vcc, 0, v185, vcc
	global_load_dwordx4 v[150:153], v[2:3], off
	global_load_dwordx4 v[154:157], v[4:5], off
	v_add_co_u32_e32 v2, vcc, s14, v184
	v_mov_b32_e32 v8, v0
	s_nop 0
	v_addc_co_u32_e32 v3, vcc, 0, v185, vcc
	v_add_co_u32_e32 v4, vcc, 0x20000, v184
	v_mov_b32_e32 v9, v0
	s_nop 0
	v_addc_co_u32_e32 v5, vcc, 0, v185, vcc
	global_load_dwordx4 v[158:161], v[2:3], off
	global_load_dwordx4 v[162:165], v[4:5], off
	v_add_co_u32_e32 v2, vcc, 0x10000, v184
	v_mov_b32_e32 v10, v0
	s_nop 0
	v_addc_co_u32_e32 v3, vcc, 0, v185, vcc
	v_add_co_u32_e32 v4, vcc, 0x30000, v182
	v_mov_b32_e32 v11, v0
	s_nop 0
	v_addc_co_u32_e32 v5, vcc, 0, v183, vcc
	global_load_dwordx4 v[166:169], v[2:3], off
	global_load_dwordx4 v[134:137], v[4:5], off
	v_add_co_u32_e32 v2, vcc, 0x20000, v182
	v_mov_b32_e32 v12, v0
	s_nop 0
	v_addc_co_u32_e32 v3, vcc, 0, v183, vcc
	v_add_co_u32_e32 v4, vcc, 0x10000, v182
	v_mov_b32_e32 v13, v0
	s_nop 0
	v_addc_co_u32_e32 v5, vcc, 0, v183, vcc
	global_load_dwordx4 v[170:173], v[2:3], off
	global_load_dwordx4 v[138:141], v[4:5], off
	global_load_dwordx4 v[174:177], v[184:185], off
	global_load_dwordx4 v[130:133], v[182:183], off
	v_mov_b32_e32 v2, v0
	v_mov_b32_e32 v3, v0
	v_mov_b32_e32 v4, v0
	v_mov_b32_e32 v5, v0
	v_mov_b64_e32 v[112:113], v[14:15]
	v_mov_b64_e32 v[128:129], v[14:15]
	s_waitcnt vmcnt(20)
	v_mov_b64_e32 v[96:97], v[14:15]
	v_mov_b64_e32 v[80:81], v[14:15]
	v_mov_b64_e32 v[64:65], v[14:15]
	v_mov_b64_e32 v[48:49], v[14:15]
	v_mov_b64_e32 v[32:33], v[14:15]
	v_mov_b64_e32 v[110:111], v[12:13]
	v_mov_b64_e32 v[108:109], v[10:11]
	v_mov_b64_e32 v[106:107], v[8:9]
	v_mov_b64_e32 v[104:105], v[6:7]
	v_mov_b64_e32 v[102:103], v[4:5]
	v_mov_b64_e32 v[100:101], v[2:3]
	v_mov_b64_e32 v[98:99], v[0:1]
	v_mov_b64_e32 v[126:127], v[12:13]
	v_mov_b64_e32 v[124:125], v[10:11]
	v_mov_b64_e32 v[122:123], v[8:9]
	v_mov_b64_e32 v[120:121], v[6:7]
	v_mov_b64_e32 v[118:119], v[4:5]
	v_mov_b64_e32 v[116:117], v[2:3]
	v_mov_b64_e32 v[114:115], v[0:1]
	v_mov_b64_e32 v[94:95], v[12:13]
	v_mov_b64_e32 v[92:93], v[10:11]
	v_mov_b64_e32 v[90:91], v[8:9]
	v_mov_b64_e32 v[88:89], v[6:7]
	v_mov_b64_e32 v[86:87], v[4:5]
	v_mov_b64_e32 v[84:85], v[2:3]
	v_mov_b64_e32 v[82:83], v[0:1]
	v_mov_b64_e32 v[78:79], v[12:13]
	v_mov_b64_e32 v[76:77], v[10:11]
	v_mov_b64_e32 v[74:75], v[8:9]
	v_mov_b64_e32 v[72:73], v[6:7]
	v_mov_b64_e32 v[70:71], v[4:5]
	v_mov_b64_e32 v[68:69], v[2:3]
	v_mov_b64_e32 v[66:67], v[0:1]
	v_mov_b64_e32 v[62:63], v[12:13]
	v_mov_b64_e32 v[60:61], v[10:11]
	v_mov_b64_e32 v[58:59], v[8:9]
	v_mov_b64_e32 v[56:57], v[6:7]
	v_mov_b64_e32 v[54:55], v[4:5]
	v_mov_b64_e32 v[52:53], v[2:3]
	v_mov_b64_e32 v[50:51], v[0:1]
	v_mov_b64_e32 v[46:47], v[12:13]
	v_mov_b64_e32 v[44:45], v[10:11]
	v_mov_b64_e32 v[42:43], v[8:9]
	v_mov_b64_e32 v[40:41], v[6:7]
	v_mov_b64_e32 v[38:39], v[4:5]
	v_mov_b64_e32 v[36:37], v[2:3]
	v_mov_b64_e32 v[34:35], v[0:1]
	v_mov_b64_e32 v[30:31], v[12:13]
	v_mov_b64_e32 v[28:29], v[10:11]
	v_mov_b64_e32 v[26:27], v[8:9]
	v_mov_b64_e32 v[24:25], v[6:7]
	v_mov_b64_e32 v[22:23], v[4:5]
	v_mov_b64_e32 v[20:21], v[2:3]
	v_mov_b64_e32 v[18:19], v[0:1]
	v_mov_b64_e32 v[16:17], v[14:15]
	v_mov_b64_e32 v[14:15], v[12:13]
	v_mov_b64_e32 v[12:13], v[10:11]
	v_mov_b64_e32 v[10:11], v[8:9]
	v_mov_b64_e32 v[8:9], v[6:7]
	v_mov_b64_e32 v[6:7], v[4:5]
	v_mov_b64_e32 v[4:5], v[2:3]
	v_mov_b64_e32 v[2:3], v[0:1]
	s_mov_b32 s5, s1
	v_readfirstlane_b32 s54, v182
	v_readfirstlane_b32 s55, v183
	v_readfirstlane_b32 s58, v184
	v_readfirstlane_b32 s59, v185
	v_subrev_u32_e32 v228, s54, v182
	v_subrev_u32_e32 v229, s58, v184
	v_xor_b32_e32 v231, 0, v187
	v_add_u32_e32 v230, v188, v231
	v_add_u32_e32 v231, v189, v231
	v_xor_b32_e32 v233, 32, v187
	v_add_u32_e32 v232, v188, v233
	v_add_u32_e32 v233, v189, v233
	v_xor_b32_e32 v235, 64, v187
	v_add_u32_e32 v234, v188, v235
	v_add_u32_e32 v235, v189, v235
	v_xor_b32_e32 v237, 0x60, v187
	v_add_u32_e32 v236, v188, v237
	v_add_u32_e32 v237, v189, v237
; DI unsigned swz(int row, int chunk) { return (unsigned)row * 128u + (unsigned)((chunk ^ ((row >> 1) & 7)) << 4); }
; #define MFMA32(a, b, c) __builtin_amdgcn_mfma_f32_32x32x16_bf16((a), (b), (c), 0, 0, 0)
;     ...
;         for (int kt = 0; kt < nk; ++kt) {
; #pragma unroll
;             for (int i = 0; i < 4; ++i) *(u32x4*)(lds + swz(lr + 32 * i, lc)) = ra[i];
; #pragma unroll
;             for (int i = 0; i < 8; ++i) *(u32x4*)(lds + 16384 + swz(lr + 32 * i, lc)) = rb[i];
;             __syncthreads();
;             if (kt + 1 < nk) {
; #pragma unroll
;                 for (int i = 0; i < 4; ++i) ra[i] = *(const u32x4*)((Au + (size_t)(32 * i) * lda + (kt + 1) * 64) + voA);
; #pragma unroll
;                 for (int i = 0; i < 8; ++i) rb[i] = *(const u32x4*)((Bu + (size_t)(32 * i) * ldb + (kt + 1) * 64) + voB);
;             }
;             __builtin_amdgcn_s_setprio(1);
; #pragma unroll 2
;             for (int ks = 0; ks < 4; ++ks) {
;                 bf16x8 af[2], bfr[4];
;                 const unsigned xo = (c0 ^ (unsigned)(2 * ks)) << 4;
; #pragma unroll
;                 for (int i = 0; i < 2; ++i) af[i] = *(const bf16x8*)(lds + (roA + xo) + i * 4096);
; #pragma unroll
;                 for (int j = 0; j < 4; ++j) bfr[j] = *(const bf16x8*)(lds + (roB + xo) + j * 4096);
; #pragma unroll
;                 for (int i = 0; i < 2; ++i)
; #pragma unroll
;                     for (int j = 0; j < 4; ++j) acc[i][j] = MFMA32(af[i], bfr[j], acc[i][j]);
;             }
;             __builtin_amdgcn_s_setprio(0);
;             __syncthreads();
.LBB0_871:
	s_mov_b32 s0, s5
	s_add_i32 s5, s5, 1
	s_cmp_lt_u32 s0, 15
	s_waitcnt vmcnt(0)
	ds_write_b128 v192, v[130:133]
	ds_write_b128 v192, v[138:141] offset:4096
	ds_write_b128 v192, v[170:173] offset:8192
	ds_write_b128 v192, v[134:137] offset:12288
	ds_write_b128 v192, v[174:177] offset:16384
	ds_write_b128 v192, v[166:169] offset:20480
	ds_write_b128 v192, v[162:165] offset:24576
	ds_write_b128 v192, v[158:161] offset:28672
	ds_write_b128 v192, v[154:157] offset:32768
	ds_write_b128 v192, v[150:153] offset:36864
	ds_write_b128 v192, v[146:149] offset:40960
	ds_write_b128 v192, v[142:145] offset:45056
	s_waitcnt lgkmcnt(0)
	s_barrier
	s_cbranch_scc0 .LBB0_873
	s_lshl_b32 s22, s5, 7
	s_setprio 1
	ds_read_b128 v[194:197], v230
	ds_read_b128 v[198:201], v231 offset:16384
	ds_read_b128 v[202:205], v230 offset:4096
	ds_read_b128 v[206:209], v231 offset:20480
	ds_read_b128 v[210:213], v231 offset:24576
	ds_read_b128 v[218:221], v231 offset:28672
	s_waitcnt lgkmcnt(4)
	v_mfma_f32_32x32x16_bf16 v[114:129], v[194:197], v[198:201], v[114:129]
	s_add_u32 s22, s54, s22
	s_addc_u32 s23, s55, 0
	global_load_dwordx4 v[130:133], v228, s[22:23]
	s_add_u32 s22, s22, 0x10000
	s_addc_u32 s23, s23, 0
	s_waitcnt lgkmcnt(2)
	v_mfma_f32_32x32x16_bf16 v[98:113], v[194:197], v[206:209], v[98:113]
	s_waitcnt lgkmcnt(1)
	v_mfma_f32_32x32x16_bf16 v[82:97], v[194:197], v[210:213], v[82:97]
	global_load_dwordx4 v[138:141], v228, s[22:23]
	s_add_u32 s22, s22, 0x10000
	s_addc_u32 s23, s23, 0
	s_waitcnt lgkmcnt(0)
	v_mfma_f32_32x32x16_bf16 v[66:81], v[194:197], v[218:221], v[66:81]
	v_mfma_f32_32x32x16_bf16 v[50:65], v[202:205], v[198:201], v[50:65]
	global_load_dwordx4 v[170:173], v228, s[22:23]
	s_add_u32 s22, s22, 0x10000
	s_addc_u32 s23, s23, 0
	v_mfma_f32_32x32x16_bf16 v[34:49], v[202:205], v[206:209], v[34:49]
	v_mfma_f32_32x32x16_bf16 v[18:33], v[202:205], v[210:213], v[18:33]
	global_load_dwordx4 v[134:137], v228, s[22:23]
	v_mfma_f32_32x32x16_bf16 v[2:17], v[202:205], v[218:221], v[2:17]
	ds_read_b128 v[194:197], v232
	ds_read_b128 v[198:201], v233 offset:16384
	ds_read_b128 v[202:205], v232 offset:4096
	ds_read_b128 v[206:209], v233 offset:20480
	ds_read_b128 v[210:213], v233 offset:24576
	ds_read_b128 v[218:221], v233 offset:28672
	s_waitcnt lgkmcnt(4)
	v_mfma_f32_32x32x16_bf16 v[114:129], v[194:197], v[198:201], v[114:129]
	s_lshl_b32 s22, s5, 7
	s_add_u32 s22, s58, s22
	s_addc_u32 s23, s59, 0
	global_load_dwordx4 v[174:177], v229, s[22:23]
	s_add_u32 s22, s22, 0x10000
	s_addc_u32 s23, s23, 0
	s_waitcnt lgkmcnt(2)
	v_mfma_f32_32x32x16_bf16 v[98:113], v[194:197], v[206:209], v[98:113]
	s_waitcnt lgkmcnt(1)
	v_mfma_f32_32x32x16_bf16 v[82:97], v[194:197], v[210:213], v[82:97]
	global_load_dwordx4 v[166:169], v229, s[22:23]
	s_add_u32 s22, s22, 0x10000
	s_addc_u32 s23, s23, 0
	s_waitcnt lgkmcnt(0)
	v_mfma_f32_32x32x16_bf16 v[66:81], v[194:197], v[218:221], v[66:81]
	v_mfma_f32_32x32x16_bf16 v[50:65], v[202:205], v[198:201], v[50:65]
	global_load_dwordx4 v[162:165], v229, s[22:23]
	s_add_u32 s22, s22, 0x10000
	s_addc_u32 s23, s23, 0
	v_mfma_f32_32x32x16_bf16 v[34:49], v[202:205], v[206:209], v[34:49]
	v_mfma_f32_32x32x16_bf16 v[18:33], v[202:205], v[210:213], v[18:33]
	global_load_dwordx4 v[158:161], v229, s[22:23]
	s_add_u32 s22, s22, 0x10000
	s_addc_u32 s23, s23, 0
	v_mfma_f32_32x32x16_bf16 v[2:17], v[202:205], v[218:221], v[2:17]
	ds_read_b128 v[194:197], v234
	ds_read_b128 v[198:201], v235 offset:16384
	ds_read_b128 v[202:205], v234 offset:4096
	ds_read_b128 v[206:209], v235 offset:20480
	ds_read_b128 v[210:213], v235 offset:24576
	ds_read_b128 v[218:221], v235 offset:28672
	s_waitcnt lgkmcnt(4)
	v_mfma_f32_32x32x16_bf16 v[114:129], v[194:197], v[198:201], v[114:129]
	global_load_dwordx4 v[154:157], v229, s[22:23]
	s_add_u32 s22, s22, 0x10000
	s_addc_u32 s23, s23, 0
	s_waitcnt lgkmcnt(2)
	v_mfma_f32_32x32x16_bf16 v[98:113], v[194:197], v[206:209], v[98:113]
	s_waitcnt lgkmcnt(1)
	v_mfma_f32_32x32x16_bf16 v[82:97], v[194:197], v[210:213], v[82:97]
	global_load_dwordx4 v[150:153], v229, s[22:23]
	s_add_u32 s22, s22, 0x10000
	s_addc_u32 s23, s23, 0
	s_waitcnt lgkmcnt(0)
	v_mfma_f32_32x32x16_bf16 v[66:81], v[194:197], v[218:221], v[66:81]
	v_mfma_f32_32x32x16_bf16 v[50:65], v[202:205], v[198:201], v[50:65]
	global_load_dwordx4 v[146:149], v229, s[22:23]
	s_add_u32 s22, s22, 0x10000
	s_addc_u32 s23, s23, 0
	v_mfma_f32_32x32x16_bf16 v[34:49], v[202:205], v[206:209], v[34:49]
	v_mfma_f32_32x32x16_bf16 v[18:33], v[202:205], v[210:213], v[18:33]
	global_load_dwordx4 v[142:145], v229, s[22:23]
	v_mfma_f32_32x32x16_bf16 v[2:17], v[202:205], v[218:221], v[2:17]
	ds_read_b128 v[194:197], v236
	ds_read_b128 v[198:201], v237 offset:16384
	ds_read_b128 v[202:205], v236 offset:4096
	ds_read_b128 v[206:209], v237 offset:20480
	ds_read_b128 v[210:213], v237 offset:24576
	ds_read_b128 v[218:221], v237 offset:28672
	s_waitcnt lgkmcnt(4)
	v_mfma_f32_32x32x16_bf16 v[114:129], v[194:197], v[198:201], v[114:129]
	s_waitcnt lgkmcnt(2)
	v_mfma_f32_32x32x16_bf16 v[98:113], v[194:197], v[206:209], v[98:113]
	s_waitcnt lgkmcnt(1)
	v_mfma_f32_32x32x16_bf16 v[82:97], v[194:197], v[210:213], v[82:97]
	s_waitcnt lgkmcnt(0)
	v_mfma_f32_32x32x16_bf16 v[66:81], v[194:197], v[218:221], v[66:81]
	v_mfma_f32_32x32x16_bf16 v[50:65], v[202:205], v[198:201], v[50:65]
	v_mfma_f32_32x32x16_bf16 v[34:49], v[202:205], v[206:209], v[34:49]
	v_mfma_f32_32x32x16_bf16 v[18:33], v[202:205], v[210:213], v[18:33]
	v_mfma_f32_32x32x16_bf16 v[2:17], v[202:205], v[218:221], v[2:17]
	s_branch .Lkint_done_874

;     ...
;     for (int lt = lb; lt < per; lt += G8) {
;         const int grp = lt / (8 * nNt), q = lt - grp * 8 * nNt, gs = (mper - grp * 8) < 8 ? (mper - grp * 8) : 8;
;         const int tn = q / gs, tm = xcd * mper + grp * 8 + (q - tn * gs);
;         const bf16_t* Au = A + (size_t)(tm * 128) * lda;
;         const bf16_t* Bu = Bt + (size_t)(tn * 256) * ldb;
;         const unsigned voA = (unsigned)(lr * lda + lc * 8), voB = (unsigned)(lr * ldb + lc * 8);
;         f32x16 acc[2][4];
; #pragma unroll
;         for (int i = 0; i < 2; ++i)
; #pragma unroll
;             for (int j = 0; j < 4; ++j)
; #pragma unroll
;                 for (int r = 0; r < 16; ++r) acc[i][j][r] = 0.f;
;         u32x4 ra[4], rb[8];
; #pragma unroll
;         for (int i = 0; i < 4; ++i) ra[i] = *(const u32x4*)((Au + (size_t)(32 * i) * lda) + voA);
; #pragma unroll
;         for (int i = 0; i < 8; ++i) rb[i] = *(const u32x4*)((Bu + (size_t)(32 * i) * ldb) + voB);
.LBB0_1251:
	s_ashr_i32 s4, s66, 31
	s_lshr_b32 s4, s4, 27
	s_add_i32 s4, s66, s4
	s_lshr_b32 s8, s4, 2
	s_andn2_b32 s4, s4, 31
	s_sub_i32 s4, s66, s4
	s_ashr_i32 s9, s4, 31
	s_and_b32 s8, s8, 0x3ffffff8
	s_lshr_b32 s9, s9, 29
	s_add_i32 s9, s4, s9
	s_add_i32 s8, s8, s3
	s_ashr_i32 s10, s9, 3
	s_add_i32 s8, s8, s4
	s_lshl_b32 s4, s10, 10
	s_lshl_b32 s8, s8, 7
	s_sub_i32 s8, s8, s4
	s_ashr_i32 s9, s8, 31
	s_lshl_b32 s10, s10, 8
	s_ashr_i32 s11, s10, 31
	s_lshl_b64 s[18:19], s[8:9], 11
	v_lshl_add_u64 v[182:183], v[178:179], 0, s[18:19]
	s_lshl_b64 s[18:19], s[10:11], 11
	v_lshl_add_u64 v[184:185], v[180:181], 0, s[18:19]
	v_add_co_u32_e32 v2, vcc, s12, v184
	v_mov_b32_e32 v14, v0
	s_nop 0
	v_addc_co_u32_e32 v3, vcc, 0, v185, vcc
	v_add_co_u32_e32 v4, vcc, s13, v184
	v_mov_b32_e32 v15, v0
	s_nop 0
	v_addc_co_u32_e32 v5, vcc, 0, v185, vcc
	global_load_dwordx4 v[142:145], v[2:3], off
	global_load_dwordx4 v[146:149], v[4:5], off
	v_add_co_u32_e32 v2, vcc, s14, v184
	v_mov_b32_e32 v1, v0
	s_nop 0
	v_addc_co_u32_e32 v3, vcc, 0, v185, vcc
	v_add_co_u32_e32 v4, vcc, s15, v184
	v_mov_b32_e32 v6, v0
	s_nop 0
	v_addc_co_u32_e32 v5, vcc, 0, v185, vcc
	global_load_dwordx4 v[150:153], v[2:3], off
	global_load_dwordx4 v[154:157], v[4:5], off
	v_add_co_u32_e32 v2, vcc, s16, v184
	v_mov_b32_e32 v7, v0
	s_nop 0
	v_addc_co_u32_e32 v3, vcc, 0, v185, vcc
	v_add_co_u32_e32 v4, vcc, 0x20000, v184
	v_mov_b32_e32 v8, v0
	s_nop 0
	v_addc_co_u32_e32 v5, vcc, 0, v185, vcc
	global_load_dwordx4 v[158:161], v[2:3], off
	global_load_dwordx4 v[162:165], v[4:5], off
	v_add_co_u32_e32 v2, vcc, 0x10000, v184
	v_mov_b32_e32 v9, v0
	s_nop 0
	v_addc_co_u32_e32 v3, vcc, 0, v185, vcc
	v_add_co_u32_e32 v4, vcc, 0x30000, v182
	v_mov_b32_e32 v10, v0
	s_nop 0
	v_addc_co_u32_e32 v5, vcc, 0, v183, vcc
	global_load_dwordx4 v[166:169], v[2:3], off
	global_load_dwordx4 v[134:137], v[4:5], off
	v_add_co_u32_e32 v2, vcc, 0x20000, v182
	v_mov_b32_e32 v11, v0
	s_nop 0
	v_addc_co_u32_e32 v3, vcc, 0, v183, vcc
	v_add_co_u32_e32 v4, vcc, 0x10000, v182
	v_mov_b32_e32 v12, v0
	s_nop 0
	v_addc_co_u32_e32 v5, vcc, 0, v183, vcc
	global_load_dwordx4 v[170:173], v[2:3], off
	global_load_dwordx4 v[138:141], v[4:5], off
	global_load_dwordx4 v[174:177], v[184:185], off
	global_load_dwordx4 v[130:133], v[182:183], off
	v_mov_b32_e32 v2, v0
	v_mov_b32_e32 v3, v0
	v_mov_b32_e32 v4, v0
	v_mov_b32_e32 v5, v0
	v_mov_b32_e32 v13, v0
	s_waitcnt vmcnt(12)
	v_mov_b64_e32 v[96:97], v[14:15]
	v_mov_b64_e32 v[128:129], v[14:15]
	v_mov_b64_e32 v[64:65], v[14:15]
	v_mov_b64_e32 v[32:33], v[14:15]
	v_mov_b64_e32 v[112:113], v[14:15]
	v_mov_b64_e32 v[80:81], v[14:15]
	v_mov_b64_e32 v[48:49], v[14:15]
	v_mov_b64_e32 v[94:95], v[12:13]
	v_mov_b64_e32 v[92:93], v[10:11]
	v_mov_b64_e32 v[90:91], v[8:9]
	v_mov_b64_e32 v[88:89], v[6:7]
	v_mov_b64_e32 v[86:87], v[4:5]
	v_mov_b64_e32 v[84:85], v[2:3]
	v_mov_b64_e32 v[82:83], v[0:1]
	v_mov_b64_e32 v[126:127], v[12:13]
	v_mov_b64_e32 v[124:125], v[10:11]
	v_mov_b64_e32 v[122:123], v[8:9]
	v_mov_b64_e32 v[120:121], v[6:7]
	v_mov_b64_e32 v[118:119], v[4:5]
	v_mov_b64_e32 v[116:117], v[2:3]
	v_mov_b64_e32 v[114:115], v[0:1]
	v_mov_b64_e32 v[62:63], v[12:13]
	v_mov_b64_e32 v[60:61], v[10:11]
	v_mov_b64_e32 v[58:59], v[8:9]
	v_mov_b64_e32 v[56:57], v[6:7]
	v_mov_b64_e32 v[54:55], v[4:5]
	v_mov_b64_e32 v[52:53], v[2:3]
	v_mov_b64_e32 v[50:51], v[0:1]
	v_mov_b64_e32 v[30:31], v[12:13]
	v_mov_b64_e32 v[28:29], v[10:11]
	v_mov_b64_e32 v[26:27], v[8:9]
	v_mov_b64_e32 v[24:25], v[6:7]
	v_mov_b64_e32 v[22:23], v[4:5]
	v_mov_b64_e32 v[20:21], v[2:3]
	v_mov_b64_e32 v[18:19], v[0:1]
	v_mov_b64_e32 v[110:111], v[12:13]
	v_mov_b64_e32 v[108:109], v[10:11]
	v_mov_b64_e32 v[106:107], v[8:9]
	v_mov_b64_e32 v[104:105], v[6:7]
	v_mov_b64_e32 v[102:103], v[4:5]
	v_mov_b64_e32 v[100:101], v[2:3]
	v_mov_b64_e32 v[98:99], v[0:1]
	v_mov_b64_e32 v[78:79], v[12:13]
	v_mov_b64_e32 v[76:77], v[10:11]
	v_mov_b64_e32 v[74:75], v[8:9]
	v_mov_b64_e32 v[72:73], v[6:7]
	v_mov_b64_e32 v[70:71], v[4:5]
	v_mov_b64_e32 v[68:69], v[2:3]
	v_mov_b64_e32 v[66:67], v[0:1]
	v_mov_b64_e32 v[46:47], v[12:13]
	v_mov_b64_e32 v[44:45], v[10:11]
	v_mov_b64_e32 v[42:43], v[8:9]
	v_mov_b64_e32 v[40:41], v[6:7]
	v_mov_b64_e32 v[38:39], v[4:5]
	v_mov_b64_e32 v[36:37], v[2:3]
	v_mov_b64_e32 v[34:35], v[0:1]
	v_mov_b64_e32 v[16:17], v[14:15]
	v_mov_b64_e32 v[14:15], v[12:13]
	v_mov_b64_e32 v[12:13], v[10:11]
	v_mov_b64_e32 v[10:11], v[8:9]
	v_mov_b64_e32 v[8:9], v[6:7]
	v_mov_b64_e32 v[6:7], v[4:5]
	v_mov_b64_e32 v[4:5], v[2:3]
	v_mov_b64_e32 v[2:3], v[0:1]
	s_mov_b32 s9, s5
	v_readfirstlane_b32 s22, v182
	v_readfirstlane_b32 s23, v183
	v_readfirstlane_b32 s68, v184
	v_readfirstlane_b32 s69, v185
	v_subrev_u32_e32 v228, s22, v182
	v_subrev_u32_e32 v229, s68, v184
	v_xor_b32_e32 v231, 0, v187
	v_add_u32_e32 v230, v188, v231
	v_add_u32_e32 v231, v189, v231
	v_xor_b32_e32 v233, 32, v187
	v_add_u32_e32 v232, v188, v233
	v_add_u32_e32 v233, v189, v233
	v_xor_b32_e32 v235, 64, v187
	v_add_u32_e32 v234, v188, v235
	v_add_u32_e32 v235, v189, v235
	v_xor_b32_e32 v237, 0x60, v187
	v_add_u32_e32 v236, v188, v237
	v_add_u32_e32 v237, v189, v237
; DI unsigned swz(int row, int chunk) { return (unsigned)row * 128u + (unsigned)((chunk ^ ((row >> 1) & 7)) << 4); }
; #define MFMA32(a, b, c) __builtin_amdgcn_mfma_f32_32x32x16_bf16((a), (b), (c), 0, 0, 0)
;     ...
;         for (int kt = 0; kt < nk; ++kt) {
; #pragma unroll
;             for (int i = 0; i < 4; ++i) *(u32x4*)(lds + swz(lr + 32 * i, lc)) = ra[i];
; #pragma unroll
;             for (int i = 0; i < 8; ++i) *(u32x4*)(lds + 16384 + swz(lr + 32 * i, lc)) = rb[i];
;             __syncthreads();
;             if (kt + 1 < nk) {
; #pragma unroll
;                 for (int i = 0; i < 4; ++i) ra[i] = *(const u32x4*)((Au + (size_t)(32 * i) * lda + (kt + 1) * 64) + voA);
; #pragma unroll
;                 for (int i = 0; i < 8; ++i) rb[i] = *(const u32x4*)((Bu + (size_t)(32 * i) * ldb + (kt + 1) * 64) + voB);
;             }
;             __builtin_amdgcn_s_setprio(1);
; #pragma unroll 2
;             for (int ks = 0; ks < 4; ++ks) {
;                 bf16x8 af[2], bfr[4];
;                 const unsigned xo = (c0 ^ (unsigned)(2 * ks)) << 4;
; #pragma unroll
;                 for (int i = 0; i < 2; ++i) af[i] = *(const bf16x8*)(lds + (roA + xo) + i * 4096);
; #pragma unroll
;                 for (int j = 0; j < 4; ++j) bfr[j] = *(const bf16x8*)(lds + (roB + xo) + j * 4096);
; #pragma unroll
;                 for (int i = 0; i < 2; ++i)
; #pragma unroll
;                     for (int j = 0; j < 4; ++j) acc[i][j] = MFMA32(af[i], bfr[j], acc[i][j]);
;             }
;             __builtin_amdgcn_s_setprio(0);
;             __syncthreads();
.LBB0_1252:
	s_mov_b32 s4, s9
	s_add_i32 s9, s9, 1
	s_cmp_lt_u32 s4, 15
	s_waitcnt vmcnt(0)
	ds_write_b128 v192, v[130:133]
	ds_write_b128 v192, v[138:141] offset:4096
	ds_write_b128 v192, v[170:173] offset:8192
	ds_write_b128 v192, v[134:137] offset:12288
	ds_write_b128 v192, v[174:177] offset:16384
	ds_write_b128 v192, v[166:169] offset:20480
	ds_write_b128 v192, v[162:165] offset:24576
	ds_write_b128 v192, v[158:161] offset:28672
	ds_write_b128 v192, v[154:157] offset:32768
	ds_write_b128 v192, v[150:153] offset:36864
	ds_write_b128 v192, v[146:149] offset:40960
	ds_write_b128 v192, v[142:145] offset:45056
	s_waitcnt lgkmcnt(0)
	s_barrier
	s_cbranch_scc0 .LBB0_1254
	s_lshl_b32 s18, s9, 7
	s_setprio 1
	ds_read_b128 v[194:197], v230
	ds_read_b128 v[198:201], v231 offset:16384
	ds_read_b128 v[202:205], v230 offset:4096
	ds_read_b128 v[206:209], v231 offset:20480
	ds_read_b128 v[210:213], v231 offset:24576
	ds_read_b128 v[218:221], v231 offset:28672
	s_waitcnt lgkmcnt(4)
	v_mfma_f32_32x32x16_bf16 v[114:129], v[194:197], v[198:201], v[114:129]
	s_add_u32 s18, s22, s18
	s_addc_u32 s19, s23, 0
	global_load_dwordx4 v[130:133], v228, s[18:19]
	s_add_u32 s18, s18, 0x10000
	s_addc_u32 s19, s19, 0
	s_waitcnt lgkmcnt(2)
	v_mfma_f32_32x32x16_bf16 v[82:97], v[194:197], v[206:209], v[82:97]
	s_waitcnt lgkmcnt(1)
	v_mfma_f32_32x32x16_bf16 v[50:65], v[194:197], v[210:213], v[50:65]
	global_load_dwordx4 v[138:141], v228, s[18:19]
	s_add_u32 s18, s18, 0x10000
	s_addc_u32 s19, s19, 0
	s_waitcnt lgkmcnt(0)
	v_mfma_f32_32x32x16_bf16 v[18:33], v[194:197], v[218:221], v[18:33]
	v_mfma_f32_32x32x16_bf16 v[98:113], v[202:205], v[198:201], v[98:113]
	global_load_dwordx4 v[170:173], v228, s[18:19]
	s_add_u32 s18, s18, 0x10000
	s_addc_u32 s19, s19, 0
	v_mfma_f32_32x32x16_bf16 v[66:81], v[202:205], v[206:209], v[66:81]
	v_mfma_f32_32x32x16_bf16 v[34:49], v[202:205], v[210:213], v[34:49]
	global_load_dwordx4 v[134:137], v228, s[18:19]
	v_mfma_f32_32x32x16_bf16 v[2:17], v[202:205], v[218:221], v[2:17]
	ds_read_b128 v[194:197], v232
	ds_read_b128 v[198:201], v233 offset:16384
	ds_read_b128 v[202:205], v232 offset:4096
	ds_read_b128 v[206:209], v233 offset:20480
	ds_read_b128 v[210:213], v233 offset:24576
	ds_read_b128 v[218:221], v233 offset:28672
	s_waitcnt lgkmcnt(4)
	v_mfma_f32_32x32x16_bf16 v[114:129], v[194:197], v[198:201], v[114:129]
	s_lshl_b32 s18, s9, 7
	s_add_u32 s18, s68, s18
	s_addc_u32 s19, s69, 0
	global_load_dwordx4 v[174:177], v229, s[18:19]
	s_add_u32 s18, s18, 0x10000
	s_addc_u32 s19, s19, 0
	s_waitcnt lgkmcnt(2)
	v_mfma_f32_32x32x16_bf16 v[82:97], v[194:197], v[206:209], v[82:97]
	s_waitcnt lgkmcnt(1)
	v_mfma_f32_32x32x16_bf16 v[50:65], v[194:197], v[210:213], v[50:65]
	global_load_dwordx4 v[166:169], v229, s[18:19]
	s_add_u32 s18, s18, 0x10000
	s_addc_u32 s19, s19, 0
	s_waitcnt lgkmcnt(0)
	v_mfma_f32_32x32x16_bf16 v[18:33], v[194:197], v[218:221], v[18:33]
	v_mfma_f32_32x32x16_bf16 v[98:113], v[202:205], v[198:201], v[98:113]
	global_load_dwordx4 v[162:165], v229, s[18:19]
	s_add_u32 s18, s18, 0x10000
	s_addc_u32 s19, s19, 0
	v_mfma_f32_32x32x16_bf16 v[66:81], v[202:205], v[206:209], v[66:81]
	v_mfma_f32_32x32x16_bf16 v[34:49], v[202:205], v[210:213], v[34:49]
	global_load_dwordx4 v[158:161], v229, s[18:19]
	s_add_u32 s18, s18, 0x10000
	s_addc_u32 s19, s19, 0
	v_mfma_f32_32x32x16_bf16 v[2:17], v[202:205], v[218:221], v[2:17]
	ds_read_b128 v[194:197], v234
	ds_read_b128 v[198:201], v235 offset:16384
	ds_read_b128 v[202:205], v234 offset:4096
	ds_read_b128 v[206:209], v235 offset:20480
	ds_read_b128 v[210:213], v235 offset:24576
	ds_read_b128 v[218:221], v235 offset:28672
	s_waitcnt lgkmcnt(4)
	v_mfma_f32_32x32x16_bf16 v[114:129], v[194:197], v[198:201], v[114:129]
	global_load_dwordx4 v[154:157], v229, s[18:19]
	s_add_u32 s18, s18, 0x10000
	s_addc_u32 s19, s19, 0
	s_waitcnt lgkmcnt(2)
	v_mfma_f32_32x32x16_bf16 v[82:97], v[194:197], v[206:209], v[82:97]
	s_waitcnt lgkmcnt(1)
	v_mfma_f32_32x32x16_bf16 v[50:65], v[194:197], v[210:213], v[50:65]
	global_load_dwordx4 v[150:153], v229, s[18:19]
	s_add_u32 s18, s18, 0x10000
	s_addc_u32 s19, s19, 0
	s_waitcnt lgkmcnt(0)
	v_mfma_f32_32x32x16_bf16 v[18:33], v[194:197], v[218:221], v[18:33]
	v_mfma_f32_32x32x16_bf16 v[98:113], v[202:205], v[198:201], v[98:113]
	global_load_dwordx4 v[146:149], v229, s[18:19]
	s_add_u32 s18, s18, 0x10000
	s_addc_u32 s19, s19, 0
	v_mfma_f32_32x32x16_bf16 v[66:81], v[202:205], v[206:209], v[66:81]
	v_mfma_f32_32x32x16_bf16 v[34:49], v[202:205], v[210:213], v[34:49]
	global_load_dwordx4 v[142:145], v229, s[18:19]
	v_mfma_f32_32x32x16_bf16 v[2:17], v[202:205], v[218:221], v[2:17]
	ds_read_b128 v[194:197], v236
	ds_read_b128 v[198:201], v237 offset:16384
	ds_read_b128 v[202:205], v236 offset:4096
	ds_read_b128 v[206:209], v237 offset:20480
	ds_read_b128 v[210:213], v237 offset:24576
	ds_read_b128 v[218:221], v237 offset:28672
	s_waitcnt lgkmcnt(4)
	v_mfma_f32_32x32x16_bf16 v[114:129], v[194:197], v[198:201], v[114:129]
	s_waitcnt lgkmcnt(2)
	v_mfma_f32_32x32x16_bf16 v[82:97], v[194:197], v[206:209], v[82:97]
	s_waitcnt lgkmcnt(1)
	v_mfma_f32_32x32x16_bf16 v[50:65], v[194:197], v[210:213], v[50:65]
	s_waitcnt lgkmcnt(0)
	v_mfma_f32_32x32x16_bf16 v[18:33], v[194:197], v[218:221], v[18:33]
	v_mfma_f32_32x32x16_bf16 v[98:113], v[202:205], v[198:201], v[98:113]
	v_mfma_f32_32x32x16_bf16 v[66:81], v[202:205], v[206:209], v[66:81]
	v_mfma_f32_32x32x16_bf16 v[34:49], v[202:205], v[210:213], v[34:49]
	v_mfma_f32_32x32x16_bf16 v[2:17], v[202:205], v[218:221], v[2:17]
	s_branch .Lkint_done_1255

;     ...
;     for (int lt = lb; lt < per; lt += G8) {
;         const int grp = lt / (8 * nNt), q = lt - grp * 8 * nNt, gs = (mper - grp * 8) < 8 ? (mper - grp * 8) : 8;
;         const int tn = q / gs, tm = xcd * mper + grp * 8 + (q - tn * gs);
;         const bf16_t* Au = A + (size_t)(tm * 128) * lda;
;         const bf16_t* Bu = Bt + (size_t)(tn * 256) * ldb;
;         const unsigned voA = (unsigned)(lr * lda + lc * 8), voB = (unsigned)(lr * ldb + lc * 8);
;         f32x16 acc[2][4];
; #pragma unroll
;         for (int i = 0; i < 2; ++i)
; #pragma unroll
;             for (int j = 0; j < 4; ++j)
; #pragma unroll
;                 for (int r = 0; r < 16; ++r) acc[i][j][r] = 0.f;
;         u32x4 ra[4], rb[8];
; #pragma unroll
;         for (int i = 0; i < 4; ++i) ra[i] = *(const u32x4*)((Au + (size_t)(32 * i) * lda) + voA);
; #pragma unroll
;         for (int i = 0; i < 8; ++i) rb[i] = *(const u32x4*)((Bu + (size_t)(32 * i) * ldb) + voB);
.LBB0_1337:
	s_mul_hi_i32 s4, s61, 0x2e8ba2e9
	s_lshr_b32 s6, s4, 31
	s_ashr_i32 s4, s4, 5
	s_add_i32 s4, s4, s6
	s_lshl_b32 s6, s4, 3
	s_mulk_i32 s4, 0xff50
	s_add_i32 s4, s4, s61
	s_ashr_i32 s7, s4, 31
	s_lshr_b32 s7, s7, 29
	s_add_i32 s7, s4, s7
	s_add_i32 s6, s6, s3
	s_ashr_i32 s8, s7, 3
	s_add_i32 s6, s6, s4
	s_lshl_b32 s4, s8, 10
	s_lshl_b32 s6, s6, 7
	s_sub_i32 s6, s6, s4
	s_ashr_i32 s7, s6, 31
	s_lshl_b64 s[18:19], s[6:7], 11
	v_lshl_add_u64 v[196:197], v[192:193], 0, s[18:19]
	v_add_co_u32_e32 v2, vcc, s10, v196
	s_lshl_b32 s8, s8, 8
	s_nop 0
	v_addc_co_u32_e32 v3, vcc, 0, v197, vcc
	v_add_co_u32_e32 v4, vcc, s11, v196
	s_ashr_i32 s9, s8, 31
	s_nop 0
	v_addc_co_u32_e32 v5, vcc, 0, v197, vcc
	s_lshl_b64 s[62:63], s[8:9], 11
	global_load_dwordx4 v[144:147], v[2:3], off
	global_load_dwordx4 v[152:155], v[4:5], off
	v_add_co_u32_e32 v2, vcc, s12, v196
	v_lshl_add_u64 v[198:199], v[194:195], 0, s[62:63]
	s_nop 0
	v_addc_co_u32_e32 v3, vcc, 0, v197, vcc
	v_add_co_u32_e32 v4, vcc, s10, v198
	global_load_dwordx4 v[148:151], v[196:197], off
	global_load_dwordx4 v[160:163], v[198:199], off
	v_addc_co_u32_e32 v5, vcc, 0, v199, vcc
	global_load_dwordx4 v[156:159], v[2:3], off
	global_load_dwordx4 v[164:167], v[4:5], off
	v_add_co_u32_e32 v2, vcc, s11, v198
	v_mov_b32_e32 v14, v0
	s_nop 0
	v_addc_co_u32_e32 v3, vcc, 0, v199, vcc
	v_add_co_u32_e32 v4, vcc, s12, v198
	v_mov_b32_e32 v15, v0
	s_nop 0
	v_addc_co_u32_e32 v5, vcc, 0, v199, vcc
	global_load_dwordx4 v[168:171], v[2:3], off
	global_load_dwordx4 v[172:175], v[4:5], off
	v_add_co_u32_e32 v2, vcc, s13, v198
	v_mov_b32_e32 v1, v0
	s_nop 0
	v_addc_co_u32_e32 v3, vcc, 0, v199, vcc
	v_add_co_u32_e32 v4, vcc, 0x50000, v198
	v_mov_b32_e32 v6, v0
	s_nop 0
	v_addc_co_u32_e32 v5, vcc, 0, v199, vcc
	global_load_dwordx4 v[176:179], v[2:3], off
	global_load_dwordx4 v[180:183], v[4:5], off
	v_add_co_u32_e32 v2, vcc, 0x60000, v198
	v_mov_b32_e32 v7, v0
	s_nop 0
	v_addc_co_u32_e32 v3, vcc, 0, v199, vcc
	v_add_co_u32_e32 v4, vcc, 0x70000, v198
	v_mov_b32_e32 v8, v0
	s_nop 0
	v_addc_co_u32_e32 v5, vcc, 0, v199, vcc
	global_load_dwordx4 v[184:187], v[2:3], off
	global_load_dwordx4 v[188:191], v[4:5], off
	v_mov_b32_e32 v2, v0
	v_mov_b32_e32 v3, v0
	v_mov_b32_e32 v4, v0
	v_mov_b32_e32 v5, v0
	v_mov_b32_e32 v9, v0
	v_mov_b32_e32 v10, v0
	v_mov_b32_e32 v11, v0
	v_mov_b32_e32 v12, v0
	v_mov_b32_e32 v13, v0
	v_mov_b64_e32 v[126:127], v[14:15]
	s_waitcnt vmcnt(12)
	v_mov_b64_e32 v[142:143], v[14:15]
	v_mov_b64_e32 v[62:63], v[14:15]
	v_mov_b64_e32 v[78:79], v[14:15]
	v_mov_b64_e32 v[94:95], v[14:15]
	v_mov_b64_e32 v[110:111], v[14:15]
	v_mov_b64_e32 v[30:31], v[14:15]
	v_mov_b64_e32 v[46:47], v[14:15]
	v_mov_b64_e32 v[124:125], v[12:13]
	v_mov_b64_e32 v[122:123], v[10:11]
	v_mov_b64_e32 v[120:121], v[8:9]
	v_mov_b64_e32 v[118:119], v[6:7]
	v_mov_b64_e32 v[116:117], v[4:5]
	v_mov_b64_e32 v[114:115], v[2:3]
	v_mov_b64_e32 v[112:113], v[0:1]
	v_mov_b64_e32 v[140:141], v[12:13]
	v_mov_b64_e32 v[138:139], v[10:11]
	v_mov_b64_e32 v[136:137], v[8:9]
	v_mov_b64_e32 v[134:135], v[6:7]
	v_mov_b64_e32 v[132:133], v[4:5]
	v_mov_b64_e32 v[130:131], v[2:3]
	v_mov_b64_e32 v[128:129], v[0:1]
	v_mov_b64_e32 v[60:61], v[12:13]
	v_mov_b64_e32 v[58:59], v[10:11]
	v_mov_b64_e32 v[56:57], v[8:9]
	v_mov_b64_e32 v[54:55], v[6:7]
	v_mov_b64_e32 v[52:53], v[4:5]
	v_mov_b64_e32 v[50:51], v[2:3]
	v_mov_b64_e32 v[48:49], v[0:1]
	v_mov_b64_e32 v[76:77], v[12:13]
	v_mov_b64_e32 v[74:75], v[10:11]
	v_mov_b64_e32 v[72:73], v[8:9]
	v_mov_b64_e32 v[70:71], v[6:7]
	v_mov_b64_e32 v[68:69], v[4:5]
	v_mov_b64_e32 v[66:67], v[2:3]
	v_mov_b64_e32 v[64:65], v[0:1]
	v_mov_b64_e32 v[92:93], v[12:13]
	v_mov_b64_e32 v[90:91], v[10:11]
	v_mov_b64_e32 v[88:89], v[8:9]
	v_mov_b64_e32 v[86:87], v[6:7]
	v_mov_b64_e32 v[84:85], v[4:5]
	v_mov_b64_e32 v[82:83], v[2:3]
	v_mov_b64_e32 v[80:81], v[0:1]
	v_mov_b64_e32 v[108:109], v[12:13]
	v_mov_b64_e32 v[106:107], v[10:11]
	v_mov_b64_e32 v[104:105], v[8:9]
	v_mov_b64_e32 v[102:103], v[6:7]
	v_mov_b64_e32 v[100:101], v[4:5]
	v_mov_b64_e32 v[98:99], v[2:3]
	v_mov_b64_e32 v[96:97], v[0:1]
	v_mov_b64_e32 v[28:29], v[12:13]
	v_mov_b64_e32 v[26:27], v[10:11]
	v_mov_b64_e32 v[24:25], v[8:9]
	v_mov_b64_e32 v[22:23], v[6:7]
	v_mov_b64_e32 v[20:21], v[4:5]
	v_mov_b64_e32 v[18:19], v[2:3]
	v_mov_b64_e32 v[16:17], v[0:1]
	v_mov_b64_e32 v[44:45], v[12:13]
	v_mov_b64_e32 v[42:43], v[10:11]
	v_mov_b64_e32 v[40:41], v[8:9]
	v_mov_b64_e32 v[38:39], v[6:7]
	v_mov_b64_e32 v[36:37], v[4:5]
	v_mov_b64_e32 v[34:35], v[2:3]
	v_mov_b64_e32 v[32:33], v[0:1]
	s_mov_b32 s7, s5
	v_readfirstlane_b32 s22, v196
	v_readfirstlane_b32 s23, v197
	v_readfirstlane_b32 s62, v198
	v_readfirstlane_b32 s63, v199
	v_subrev_u32_e32 v228, s22, v196
	v_subrev_u32_e32 v229, s62, v198
	v_xor_b32_e32 v231, 0, v201
	v_add_u32_e32 v230, v202, v231
	v_add_u32_e32 v231, v203, v231
	v_xor_b32_e32 v233, 32, v201
	v_add_u32_e32 v232, v202, v233
	v_add_u32_e32 v233, v203, v233
	v_xor_b32_e32 v235, 64, v201
	v_add_u32_e32 v234, v202, v235
	v_add_u32_e32 v235, v203, v235
	v_xor_b32_e32 v237, 0x60, v201
	v_add_u32_e32 v236, v202, v237
	v_add_u32_e32 v237, v203, v237
; DI unsigned swz(int row, int chunk) { return (unsigned)row * 128u + (unsigned)((chunk ^ ((row >> 1) & 7)) << 4); }
; #define MFMA32(a, b, c) __builtin_amdgcn_mfma_f32_32x32x16_bf16((a), (b), (c), 0, 0, 0)
;     ...
;         for (int kt = 0; kt < nk; ++kt) {
; #pragma unroll
;             for (int i = 0; i < 4; ++i) *(u32x4*)(lds + swz(lr + 32 * i, lc)) = ra[i];
; #pragma unroll
;             for (int i = 0; i < 8; ++i) *(u32x4*)(lds + 16384 + swz(lr + 32 * i, lc)) = rb[i];
;             __syncthreads();
;             if (kt + 1 < nk) {
; #pragma unroll
;                 for (int i = 0; i < 4; ++i) ra[i] = *(const u32x4*)((Au + (size_t)(32 * i) * lda + (kt + 1) * 64) + voA);
; #pragma unroll
;                 for (int i = 0; i < 8; ++i) rb[i] = *(const u32x4*)((Bu + (size_t)(32 * i) * ldb + (kt + 1) * 64) + voB);
;             }
;             __builtin_amdgcn_s_setprio(1);
; #pragma unroll 2
;             for (int ks = 0; ks < 4; ++ks) {
;                 bf16x8 af[2], bfr[4];
;                 const unsigned xo = (c0 ^ (unsigned)(2 * ks)) << 4;
; #pragma unroll
;                 for (int i = 0; i < 2; ++i) af[i] = *(const bf16x8*)(lds + (roA + xo) + i * 4096);
; #pragma unroll
;                 for (int j = 0; j < 4; ++j) bfr[j] = *(const bf16x8*)(lds + (roB + xo) + j * 4096);
; #pragma unroll
;                 for (int i = 0; i < 2; ++i)
; #pragma unroll
;                     for (int j = 0; j < 4; ++j) acc[i][j] = MFMA32(af[i], bfr[j], acc[i][j]);
;             }
;             __builtin_amdgcn_s_setprio(0);
;             __syncthreads();
.LBB0_1338:
	s_mov_b32 s4, s7
	s_add_i32 s7, s7, 1
	s_cmp_lg_u32 s4, 15
	s_waitcnt vmcnt(9)
	ds_write_b128 v206, v[148:151]
	ds_write_b128 v206, v[144:147] offset:4096
	ds_write_b128 v206, v[152:155] offset:8192
	s_waitcnt vmcnt(7)
	ds_write_b128 v206, v[156:159] offset:12288
	ds_write_b128 v206, v[160:163] offset:16384
	s_waitcnt vmcnt(6)
	ds_write_b128 v206, v[164:167] offset:20480
	s_waitcnt vmcnt(5)
	ds_write_b128 v206, v[168:171] offset:24576
	s_waitcnt vmcnt(4)
	ds_write_b128 v206, v[172:175] offset:28672
	s_waitcnt vmcnt(3)
	ds_write_b128 v206, v[176:179] offset:32768
	s_waitcnt vmcnt(2)
	ds_write_b128 v206, v[180:183] offset:36864
	s_waitcnt vmcnt(1)
	ds_write_b128 v206, v[184:187] offset:40960
	s_waitcnt vmcnt(0)
	ds_write_b128 v206, v[188:191] offset:45056
	s_waitcnt lgkmcnt(0)
	s_barrier
	s_cbranch_scc0 .LBB0_1340
	s_lshl_b32 s18, s7, 7
	s_setprio 1
	ds_read_b128 v[2:5], v230
	ds_read_b128 v[6:9], v231 offset:16384
	ds_read_b128 v[10:13], v230 offset:4096
	ds_read_b128 v[208:211], v231 offset:20480
	ds_read_b128 v[212:215], v231 offset:24576
	ds_read_b128 v[218:221], v231 offset:28672
	s_waitcnt lgkmcnt(4)
	v_mfma_f32_32x32x16_bf16 v[128:143], v[2:5], v[6:9], v[128:143]
	s_add_u32 s18, s22, s18
	s_addc_u32 s19, s23, 0
	global_load_dwordx4 v[148:151], v228, s[18:19]
	s_add_u32 s18, s18, 0x10000
	s_addc_u32 s19, s19, 0
	s_waitcnt lgkmcnt(2)
	v_mfma_f32_32x32x16_bf16 v[112:127], v[2:5], v[208:211], v[112:127]
	s_waitcnt lgkmcnt(1)
	v_mfma_f32_32x32x16_bf16 v[48:63], v[2:5], v[212:215], v[48:63]
	global_load_dwordx4 v[144:147], v228, s[18:19]
	s_add_u32 s18, s18, 0x10000
	s_addc_u32 s19, s19, 0
	s_waitcnt lgkmcnt(0)
	v_mfma_f32_32x32x16_bf16 v[64:79], v[2:5], v[218:221], v[64:79]
	v_mfma_f32_32x32x16_bf16 v[80:95], v[10:13], v[6:9], v[80:95]
	global_load_dwordx4 v[152:155], v228, s[18:19]
	s_add_u32 s18, s18, 0x10000
	s_addc_u32 s19, s19, 0
	v_mfma_f32_32x32x16_bf16 v[96:111], v[10:13], v[208:211], v[96:111]
	v_mfma_f32_32x32x16_bf16 v[16:31], v[10:13], v[212:215], v[16:31]
	global_load_dwordx4 v[156:159], v228, s[18:19]
	v_mfma_f32_32x32x16_bf16 v[32:47], v[10:13], v[218:221], v[32:47]
	ds_read_b128 v[2:5], v232
	ds_read_b128 v[6:9], v233 offset:16384
	ds_read_b128 v[10:13], v232 offset:4096
	ds_read_b128 v[208:211], v233 offset:20480
	ds_read_b128 v[212:215], v233 offset:24576
	ds_read_b128 v[218:221], v233 offset:28672
	s_waitcnt lgkmcnt(4)
	v_mfma_f32_32x32x16_bf16 v[128:143], v[2:5], v[6:9], v[128:143]
	s_lshl_b32 s18, s7, 7
	s_add_u32 s18, s62, s18
	s_addc_u32 s19, s63, 0
	global_load_dwordx4 v[160:163], v229, s[18:19]
	s_add_u32 s18, s18, 0x10000
	s_addc_u32 s19, s19, 0
	s_waitcnt lgkmcnt(2)
	v_mfma_f32_32x32x16_bf16 v[112:127], v[2:5], v[208:211], v[112:127]
	s_waitcnt lgkmcnt(1)
	v_mfma_f32_32x32x16_bf16 v[48:63], v[2:5], v[212:215], v[48:63]
	global_load_dwordx4 v[164:167], v229, s[18:19]
	s_add_u32 s18, s18, 0x10000
	s_addc_u32 s19, s19, 0
	s_waitcnt lgkmcnt(0)
	v_mfma_f32_32x32x16_bf16 v[64:79], v[2:5], v[218:221], v[64:79]
	v_mfma_f32_32x32x16_bf16 v[80:95], v[10:13], v[6:9], v[80:95]
	global_load_dwordx4 v[168:171], v229, s[18:19]
	s_add_u32 s18, s18, 0x10000
	s_addc_u32 s19, s19, 0
	v_mfma_f32_32x32x16_bf16 v[96:111], v[10:13], v[208:211], v[96:111]
	v_mfma_f32_32x32x16_bf16 v[16:31], v[10:13], v[212:215], v[16:31]
	global_load_dwordx4 v[172:175], v229, s[18:19]
	s_add_u32 s18, s18, 0x10000
	s_addc_u32 s19, s19, 0
	v_mfma_f32_32x32x16_bf16 v[32:47], v[10:13], v[218:221], v[32:47]
	ds_read_b128 v[2:5], v234
	ds_read_b128 v[6:9], v235 offset:16384
	ds_read_b128 v[10:13], v234 offset:4096
	ds_read_b128 v[208:211], v235 offset:20480
	ds_read_b128 v[212:215], v235 offset:24576
	ds_read_b128 v[218:221], v235 offset:28672
	s_waitcnt lgkmcnt(4)
	v_mfma_f32_32x32x16_bf16 v[128:143], v[2:5], v[6:9], v[128:143]
	global_load_dwordx4 v[176:179], v229, s[18:19]
	s_add_u32 s18, s18, 0x10000
	s_addc_u32 s19, s19, 0
	s_waitcnt lgkmcnt(2)
	v_mfma_f32_32x32x16_bf16 v[112:127], v[2:5], v[208:211], v[112:127]
	s_waitcnt lgkmcnt(1)
	v_mfma_f32_32x32x16_bf16 v[48:63], v[2:5], v[212:215], v[48:63]
	global_load_dwordx4 v[180:183], v229, s[18:19]
	s_add_u32 s18, s18, 0x10000
	s_addc_u32 s19, s19, 0
	s_waitcnt lgkmcnt(0)
	v_mfma_f32_32x32x16_bf16 v[64:79], v[2:5], v[218:221], v[64:79]
	v_mfma_f32_32x32x16_bf16 v[80:95], v[10:13], v[6:9], v[80:95]
	global_load_dwordx4 v[184:187], v229, s[18:19]
	s_add_u32 s18, s18, 0x10000
	s_addc_u32 s19, s19, 0
	v_mfma_f32_32x32x16_bf16 v[96:111], v[10:13], v[208:211], v[96:111]
	v_mfma_f32_32x32x16_bf16 v[16:31], v[10:13], v[212:215], v[16:31]
	global_load_dwordx4 v[188:191], v229, s[18:19]
	v_mfma_f32_32x32x16_bf16 v[32:47], v[10:13], v[218:221], v[32:47]
	ds_read_b128 v[2:5], v236
	ds_read_b128 v[6:9], v237 offset:16384
	ds_read_b128 v[10:13], v236 offset:4096
	ds_read_b128 v[208:211], v237 offset:20480
	ds_read_b128 v[212:215], v237 offset:24576
	ds_read_b128 v[218:221], v237 offset:28672
	s_waitcnt lgkmcnt(4)
	v_mfma_f32_32x32x16_bf16 v[128:143], v[2:5], v[6:9], v[128:143]
	s_waitcnt lgkmcnt(2)
	v_mfma_f32_32x32x16_bf16 v[112:127], v[2:5], v[208:211], v[112:127]
	s_waitcnt lgkmcnt(1)
	v_mfma_f32_32x32x16_bf16 v[48:63], v[2:5], v[212:215], v[48:63]
	s_waitcnt lgkmcnt(0)
	v_mfma_f32_32x32x16_bf16 v[64:79], v[2:5], v[218:221], v[64:79]
	v_mfma_f32_32x32x16_bf16 v[80:95], v[10:13], v[6:9], v[80:95]
	v_mfma_f32_32x32x16_bf16 v[96:111], v[10:13], v[208:211], v[96:111]
	v_mfma_f32_32x32x16_bf16 v[16:31], v[10:13], v[212:215], v[16:31]
	v_mfma_f32_32x32x16_bf16 v[32:47], v[10:13], v[218:221], v[32:47]
	s_branch .Lkint_done_1341

;     ...
;     for (int lt = lb; lt < per; lt += G8) {
;         const int grp = lt / (8 * nNt), q = lt - grp * 8 * nNt, gs = (mper - grp * 8) < 8 ? (mper - grp * 8) : 8;
;         const int tn = q / gs, tm = xcd * mper + grp * 8 + (q - tn * gs);
;         const bf16_t* Au = A + (size_t)(tm * 128) * lda;
;         const bf16_t* Bu = Bt + (size_t)(tn * 256) * ldb;
;         const unsigned voA = (unsigned)(lr * lda + lc * 8), voB = (unsigned)(lr * ldb + lc * 8);
;         f32x16 acc[2][4];
; #pragma unroll
;         for (int i = 0; i < 2; ++i)
; #pragma unroll
;             for (int j = 0; j < 4; ++j)
; #pragma unroll
;                 for (int r = 0; r < 16; ++r) acc[i][j][r] = 0.f;
;         u32x4 ra[4], rb[8];
; #pragma unroll
;         for (int i = 0; i < 4; ++i) ra[i] = *(const u32x4*)((Au + (size_t)(32 * i) * lda) + voA);
; #pragma unroll
;         for (int i = 0; i < 8; ++i) rb[i] = *(const u32x4*)((Bu + (size_t)(32 * i) * ldb) + voB);
.LBB0_1383:
	s_ashr_i32 s0, s85, 31
	s_lshr_b32 s0, s0, 27
	s_add_i32 s0, s85, s0
	s_lshr_b32 s18, s0, 2
	s_andn2_b32 s0, s0, 31
	s_sub_i32 s0, s85, s0
	s_ashr_i32 s19, s0, 31
	s_and_b32 s18, s18, 0x3ffffff8
	s_lshr_b32 s19, s19, 29
	s_add_i32 s19, s0, s19
	s_add_i32 s18, s18, s4
	s_ashr_i32 s19, s19, 3
	s_add_i32 s18, s18, s0
	s_lshl_b32 s0, s19, 10
	s_lshl_b32 s18, s18, 7
	s_lshl_b32 s58, s19, 8
	s_sub_i32 s57, s18, s0
	v_mad_i64_i32 v[184:185], s[18:19], s58, v192, v[180:181]
	v_add_co_u32_e32 v2, vcc, s5, v184
	v_mad_i64_i32 v[182:183], s[18:19], s57, v192, v[178:179]
	s_nop 0
	v_addc_co_u32_e32 v3, vcc, 0, v185, vcc
	v_add_co_u32_e32 v4, vcc, s6, v184
	v_mov_b32_e32 v14, v0
	s_nop 0
	v_addc_co_u32_e32 v5, vcc, 0, v185, vcc
	global_load_dwordx4 v[142:145], v[2:3], off
	global_load_dwordx4 v[146:149], v[4:5], off
	v_add_co_u32_e32 v2, vcc, s7, v184
	v_mov_b32_e32 v15, v0
	s_nop 0
	v_addc_co_u32_e32 v3, vcc, 0, v185, vcc
	v_add_co_u32_e32 v4, vcc, s8, v184
	v_mov_b32_e32 v1, v0
	s_nop 0
	v_addc_co_u32_e32 v5, vcc, 0, v185, vcc
	global_load_dwordx4 v[150:153], v[2:3], off
	global_load_dwordx4 v[154:157], v[4:5], off
	v_add_co_u32_e32 v2, vcc, s9, v184
	v_mov_b32_e32 v6, v0
	s_nop 0
	v_addc_co_u32_e32 v3, vcc, 0, v185, vcc
	v_add_co_u32_e32 v4, vcc, 0x58000, v184
	v_mov_b32_e32 v7, v0
	s_nop 0
	v_addc_co_u32_e32 v5, vcc, 0, v185, vcc
	global_load_dwordx4 v[158:161], v[2:3], off
	global_load_dwordx4 v[162:165], v[4:5], off
	v_add_co_u32_e32 v2, vcc, 0x2c000, v184
	v_mov_b32_e32 v8, v0
	s_nop 0
	v_addc_co_u32_e32 v3, vcc, 0, v185, vcc
	v_add_co_u32_e32 v4, vcc, 0x84000, v182
	v_mov_b32_e32 v9, v0
	s_nop 0
	v_addc_co_u32_e32 v5, vcc, 0, v183, vcc
	global_load_dwordx4 v[166:169], v[2:3], off
	global_load_dwordx4 v[134:137], v[4:5], off
	v_add_co_u32_e32 v2, vcc, 0x58000, v182
	v_mov_b32_e32 v10, v0
	s_nop 0
	v_addc_co_u32_e32 v3, vcc, 0, v183, vcc
	v_add_co_u32_e32 v4, vcc, 0x2c000, v182
	v_mov_b32_e32 v11, v0
	s_nop 0
	v_addc_co_u32_e32 v5, vcc, 0, v183, vcc
	global_load_dwordx4 v[170:173], v[2:3], off
	global_load_dwordx4 v[138:141], v[4:5], off
	global_load_dwordx4 v[174:177], v[184:185], off
	global_load_dwordx4 v[130:133], v[182:183], off
	v_mov_b32_e32 v2, v0
	v_mov_b32_e32 v3, v0
	v_mov_b32_e32 v4, v0
	v_mov_b32_e32 v5, v0
	v_mov_b32_e32 v12, v0
	v_mov_b32_e32 v13, v0
	s_waitcnt vmcnt(12)
	v_mov_b64_e32 v[96:97], v[14:15]
	v_mov_b64_e32 v[128:129], v[14:15]
	v_mov_b64_e32 v[64:65], v[14:15]
	v_mov_b64_e32 v[32:33], v[14:15]
	v_mov_b64_e32 v[112:113], v[14:15]
	v_mov_b64_e32 v[80:81], v[14:15]
	v_mov_b64_e32 v[48:49], v[14:15]
	v_mov_b64_e32 v[94:95], v[12:13]
	v_mov_b64_e32 v[92:93], v[10:11]
	v_mov_b64_e32 v[90:91], v[8:9]
	v_mov_b64_e32 v[88:89], v[6:7]
	v_mov_b64_e32 v[86:87], v[4:5]
	v_mov_b64_e32 v[84:85], v[2:3]
	v_mov_b64_e32 v[82:83], v[0:1]
	v_mov_b64_e32 v[126:127], v[12:13]
	v_mov_b64_e32 v[124:125], v[10:11]
	v_mov_b64_e32 v[122:123], v[8:9]
	v_mov_b64_e32 v[120:121], v[6:7]
	v_mov_b64_e32 v[118:119], v[4:5]
	v_mov_b64_e32 v[116:117], v[2:3]
	v_mov_b64_e32 v[114:115], v[0:1]
	v_mov_b64_e32 v[62:63], v[12:13]
	v_mov_b64_e32 v[60:61], v[10:11]
	v_mov_b64_e32 v[58:59], v[8:9]
	v_mov_b64_e32 v[56:57], v[6:7]
	v_mov_b64_e32 v[54:55], v[4:5]
	v_mov_b64_e32 v[52:53], v[2:3]
	v_mov_b64_e32 v[50:51], v[0:1]
	v_mov_b64_e32 v[30:31], v[12:13]
	v_mov_b64_e32 v[28:29], v[10:11]
	v_mov_b64_e32 v[26:27], v[8:9]
	v_mov_b64_e32 v[24:25], v[6:7]
	v_mov_b64_e32 v[22:23], v[4:5]
	v_mov_b64_e32 v[20:21], v[2:3]
	v_mov_b64_e32 v[18:19], v[0:1]
	v_mov_b64_e32 v[110:111], v[12:13]
	v_mov_b64_e32 v[108:109], v[10:11]
	v_mov_b64_e32 v[106:107], v[8:9]
	v_mov_b64_e32 v[104:105], v[6:7]
	v_mov_b64_e32 v[102:103], v[4:5]
	v_mov_b64_e32 v[100:101], v[2:3]
	v_mov_b64_e32 v[98:99], v[0:1]
	v_mov_b64_e32 v[78:79], v[12:13]
	v_mov_b64_e32 v[76:77], v[10:11]
	v_mov_b64_e32 v[74:75], v[8:9]
	v_mov_b64_e32 v[72:73], v[6:7]
	v_mov_b64_e32 v[70:71], v[4:5]
	v_mov_b64_e32 v[68:69], v[2:3]
	v_mov_b64_e32 v[66:67], v[0:1]
	v_mov_b64_e32 v[46:47], v[12:13]
	v_mov_b64_e32 v[44:45], v[10:11]
	v_mov_b64_e32 v[42:43], v[8:9]
	v_mov_b64_e32 v[40:41], v[6:7]
	v_mov_b64_e32 v[38:39], v[4:5]
	v_mov_b64_e32 v[36:37], v[2:3]
	v_mov_b64_e32 v[34:35], v[0:1]
	v_mov_b64_e32 v[16:17], v[14:15]
	v_mov_b64_e32 v[14:15], v[12:13]
	v_mov_b64_e32 v[12:13], v[10:11]
	v_mov_b64_e32 v[10:11], v[8:9]
	v_mov_b64_e32 v[8:9], v[6:7]
	v_mov_b64_e32 v[6:7], v[4:5]
	v_mov_b64_e32 v[4:5], v[2:3]
	v_mov_b64_e32 v[2:3], v[0:1]
	s_mov_b32 s59, s1
	v_readfirstlane_b32 s62, v182
	v_readfirstlane_b32 s63, v183
	v_readfirstlane_b32 s64, v184
	v_readfirstlane_b32 s65, v185
	v_subrev_u32_e32 v228, s62, v182
	v_subrev_u32_e32 v229, s64, v184
	v_xor_b32_e32 v231, 0, v187
	v_add_u32_e32 v230, v188, v231
	v_add_u32_e32 v231, v189, v231
	v_xor_b32_e32 v233, 32, v187
	v_add_u32_e32 v232, v188, v233
	v_add_u32_e32 v233, v189, v233
	v_xor_b32_e32 v235, 64, v187
	v_add_u32_e32 v234, v188, v235
	v_add_u32_e32 v235, v189, v235
	v_xor_b32_e32 v237, 0x60, v187
	v_add_u32_e32 v236, v188, v237
	v_add_u32_e32 v237, v189, v237
; DI unsigned swz(int row, int chunk) { return (unsigned)row * 128u + (unsigned)((chunk ^ ((row >> 1) & 7)) << 4); }
; #define MFMA32(a, b, c) __builtin_amdgcn_mfma_f32_32x32x16_bf16((a), (b), (c), 0, 0, 0)
;     ...
;         for (int kt = 0; kt < nk; ++kt) {
; #pragma unroll
;             for (int i = 0; i < 4; ++i) *(u32x4*)(lds + swz(lr + 32 * i, lc)) = ra[i];
; #pragma unroll
;             for (int i = 0; i < 8; ++i) *(u32x4*)(lds + 16384 + swz(lr + 32 * i, lc)) = rb[i];
;             __syncthreads();
;             if (kt + 1 < nk) {
; #pragma unroll
;                 for (int i = 0; i < 4; ++i) ra[i] = *(const u32x4*)((Au + (size_t)(32 * i) * lda + (kt + 1) * 64) + voA);
; #pragma unroll
;                 for (int i = 0; i < 8; ++i) rb[i] = *(const u32x4*)((Bu + (size_t)(32 * i) * ldb + (kt + 1) * 64) + voB);
;             }
;             __builtin_amdgcn_s_setprio(1);
; #pragma unroll 2
;             for (int ks = 0; ks < 4; ++ks) {
;                 bf16x8 af[2], bfr[4];
;                 const unsigned xo = (c0 ^ (unsigned)(2 * ks)) << 4;
; #pragma unroll
;                 for (int i = 0; i < 2; ++i) af[i] = *(const bf16x8*)(lds + (roA + xo) + i * 4096);
; #pragma unroll
;                 for (int j = 0; j < 4; ++j) bfr[j] = *(const bf16x8*)(lds + (roB + xo) + j * 4096);
; #pragma unroll
;                 for (int i = 0; i < 2; ++i)
; #pragma unroll
;                     for (int j = 0; j < 4; ++j) acc[i][j] = MFMA32(af[i], bfr[j], acc[i][j]);
;             }
;             __builtin_amdgcn_s_setprio(0);
;             __syncthreads();
.LBB0_1384:
	s_mov_b32 s0, s59
	s_add_i32 s59, s59, 1
	s_cmp_lt_u32 s0, 43
	s_waitcnt vmcnt(0)
	ds_write_b128 v193, v[130:133]
	ds_write_b128 v193, v[138:141] offset:4096
	ds_write_b128 v193, v[170:173] offset:8192
	ds_write_b128 v193, v[134:137] offset:12288
	ds_write_b128 v193, v[174:177] offset:16384
	ds_write_b128 v193, v[166:169] offset:20480
	ds_write_b128 v193, v[162:165] offset:24576
	ds_write_b128 v193, v[158:161] offset:28672
	ds_write_b128 v193, v[154:157] offset:32768
	ds_write_b128 v193, v[150:153] offset:36864
	ds_write_b128 v193, v[146:149] offset:40960
	ds_write_b128 v193, v[142:145] offset:45056
	s_waitcnt lgkmcnt(0)
	s_barrier
	s_cbranch_scc0 .LBB0_1386
	s_lshl_b32 s60, s59, 7
	s_setprio 1
	ds_read_b128 v[194:197], v230
	ds_read_b128 v[198:201], v231 offset:16384
	ds_read_b128 v[202:205], v230 offset:4096
	ds_read_b128 v[206:209], v231 offset:20480
	ds_read_b128 v[210:213], v231 offset:24576
	ds_read_b128 v[218:221], v231 offset:28672
	s_waitcnt lgkmcnt(4)
	v_mfma_f32_32x32x16_bf16 v[114:129], v[194:197], v[198:201], v[114:129]
	s_add_u32 s60, s62, s60
	s_addc_u32 s61, s63, 0
	global_load_dwordx4 v[130:133], v228, s[60:61]
	s_add_u32 s60, s60, 0x2c000
	s_addc_u32 s61, s61, 0
	s_waitcnt lgkmcnt(2)
	v_mfma_f32_32x32x16_bf16 v[82:97], v[194:197], v[206:209], v[82:97]
	s_waitcnt lgkmcnt(1)
	v_mfma_f32_32x32x16_bf16 v[50:65], v[194:197], v[210:213], v[50:65]
	global_load_dwordx4 v[138:141], v228, s[60:61]
	s_add_u32 s60, s60, 0x2c000
	s_addc_u32 s61, s61, 0
	s_waitcnt lgkmcnt(0)
	v_mfma_f32_32x32x16_bf16 v[18:33], v[194:197], v[218:221], v[18:33]
	v_mfma_f32_32x32x16_bf16 v[98:113], v[202:205], v[198:201], v[98:113]
	global_load_dwordx4 v[170:173], v228, s[60:61]
	s_add_u32 s60, s60, 0x2c000
	s_addc_u32 s61, s61, 0
	v_mfma_f32_32x32x16_bf16 v[66:81], v[202:205], v[206:209], v[66:81]
	v_mfma_f32_32x32x16_bf16 v[34:49], v[202:205], v[210:213], v[34:49]
	global_load_dwordx4 v[134:137], v228, s[60:61]
	v_mfma_f32_32x32x16_bf16 v[2:17], v[202:205], v[218:221], v[2:17]
	ds_read_b128 v[194:197], v232
	ds_read_b128 v[198:201], v233 offset:16384
	ds_read_b128 v[202:205], v232 offset:4096
	ds_read_b128 v[206:209], v233 offset:20480
	ds_read_b128 v[210:213], v233 offset:24576
	ds_read_b128 v[218:221], v233 offset:28672
	s_waitcnt lgkmcnt(4)
	v_mfma_f32_32x32x16_bf16 v[114:129], v[194:197], v[198:201], v[114:129]
	s_lshl_b32 s60, s59, 7
	s_add_u32 s60, s64, s60
	s_addc_u32 s61, s65, 0
	global_load_dwordx4 v[174:177], v229, s[60:61]
	s_add_u32 s60, s60, 0x2c000
	s_addc_u32 s61, s61, 0
	s_waitcnt lgkmcnt(2)
	v_mfma_f32_32x32x16_bf16 v[82:97], v[194:197], v[206:209], v[82:97]
	s_waitcnt lgkmcnt(1)
	v_mfma_f32_32x32x16_bf16 v[50:65], v[194:197], v[210:213], v[50:65]
	global_load_dwordx4 v[166:169], v229, s[60:61]
	s_add_u32 s60, s60, 0x2c000
	s_addc_u32 s61, s61, 0
	s_waitcnt lgkmcnt(0)
	v_mfma_f32_32x32x16_bf16 v[18:33], v[194:197], v[218:221], v[18:33]
	v_mfma_f32_32x32x16_bf16 v[98:113], v[202:205], v[198:201], v[98:113]
	global_load_dwordx4 v[162:165], v229, s[60:61]
	s_add_u32 s60, s60, 0x2c000
	s_addc_u32 s61, s61, 0
	v_mfma_f32_32x32x16_bf16 v[66:81], v[202:205], v[206:209], v[66:81]
	v_mfma_f32_32x32x16_bf16 v[34:49], v[202:205], v[210:213], v[34:49]
	global_load_dwordx4 v[158:161], v229, s[60:61]
	s_add_u32 s60, s60, 0x2c000
	s_addc_u32 s61, s61, 0
	v_mfma_f32_32x32x16_bf16 v[2:17], v[202:205], v[218:221], v[2:17]
	ds_read_b128 v[194:197], v234
	ds_read_b128 v[198:201], v235 offset:16384
	ds_read_b128 v[202:205], v234 offset:4096
	ds_read_b128 v[206:209], v235 offset:20480
	ds_read_b128 v[210:213], v235 offset:24576
	ds_read_b128 v[218:221], v235 offset:28672
	s_waitcnt lgkmcnt(4)
	v_mfma_f32_32x32x16_bf16 v[114:129], v[194:197], v[198:201], v[114:129]
	global_load_dwordx4 v[154:157], v229, s[60:61]
	s_add_u32 s60, s60, 0x2c000
	s_addc_u32 s61, s61, 0
	s_waitcnt lgkmcnt(2)
	v_mfma_f32_32x32x16_bf16 v[82:97], v[194:197], v[206:209], v[82:97]
	s_waitcnt lgkmcnt(1)
	v_mfma_f32_32x32x16_bf16 v[50:65], v[194:197], v[210:213], v[50:65]
	global_load_dwordx4 v[150:153], v229, s[60:61]
	s_add_u32 s60, s60, 0x2c000
	s_addc_u32 s61, s61, 0
	s_waitcnt lgkmcnt(0)
	v_mfma_f32_32x32x16_bf16 v[18:33], v[194:197], v[218:221], v[18:33]
	v_mfma_f32_32x32x16_bf16 v[98:113], v[202:205], v[198:201], v[98:113]
	global_load_dwordx4 v[146:149], v229, s[60:61]
	s_add_u32 s60, s60, 0x2c000
	s_addc_u32 s61, s61, 0
	v_mfma_f32_32x32x16_bf16 v[66:81], v[202:205], v[206:209], v[66:81]
	v_mfma_f32_32x32x16_bf16 v[34:49], v[202:205], v[210:213], v[34:49]
	global_load_dwordx4 v[142:145], v229, s[60:61]
	v_mfma_f32_32x32x16_bf16 v[2:17], v[202:205], v[218:221], v[2:17]
	ds_read_b128 v[194:197], v236
	ds_read_b128 v[198:201], v237 offset:16384
	ds_read_b128 v[202:205], v236 offset:4096
	ds_read_b128 v[206:209], v237 offset:20480
	ds_read_b128 v[210:213], v237 offset:24576
	ds_read_b128 v[218:221], v237 offset:28672
	s_waitcnt lgkmcnt(4)
	v_mfma_f32_32x32x16_bf16 v[114:129], v[194:197], v[198:201], v[114:129]
	s_waitcnt lgkmcnt(2)
	v_mfma_f32_32x32x16_bf16 v[82:97], v[194:197], v[206:209], v[82:97]
	s_waitcnt lgkmcnt(1)
	v_mfma_f32_32x32x16_bf16 v[50:65], v[194:197], v[210:213], v[50:65]
	s_waitcnt lgkmcnt(0)
	v_mfma_f32_32x32x16_bf16 v[18:33], v[194:197], v[218:221], v[18:33]
	v_mfma_f32_32x32x16_bf16 v[98:113], v[202:205], v[198:201], v[98:113]
	v_mfma_f32_32x32x16_bf16 v[66:81], v[202:205], v[206:209], v[66:81]
	v_mfma_f32_32x32x16_bf16 v[34:49], v[202:205], v[210:213], v[34:49]
	v_mfma_f32_32x32x16_bf16 v[2:17], v[202:205], v[218:221], v[2:17]
	s_branch .Lkint_done_1387
